# v31 + extra s_setprio 0/1 dip after the 8th MFMA of every 16-MFMA group in the K-loops
# speedup vs baseline: 1.0050x; 1.0050x over previous
; #define PG8_STAGE(bufoff, gbase, voff) do { _Pragma("unroll") for (int _i = 0; _i < 2; ++_i) \
;         __builtin_amdgcn_global_load_lds((const unsigned*)((const char*)(gbase) + (voff)[_i]), (LAS unsigned*)(lds + (bufoff) + ldsw + _i * 8192), 16, 0, PG8_AUX); } while (0)
; #define PG8_LDA(dst, b, h) do { _Pragma("unroll") for (int m = 0; m < 4; ++m) _Pragma("unroll") for (int k = 0; k < 2; ++k) dst[m][k] = *(const LAS bf16x8*)(lds + PG8_SA(b, h) + aoff + m * 2048 + k * 1024); } while (0)
; #define PG8_LDB(dst, b, h) do { _Pragma("unroll") for (int n = 0; n < 2; ++n) _Pragma("unroll") for (int k = 0; k < 2; ++k) dst[n][k] = *(const LAS bf16x8*)(lds + PG8_SB(b, h) + boff + n * 2048 + k * 1024); } while (0)
; #define PG8_MMA(ai, bj, At, Bt) do { __builtin_amdgcn_s_setprio(1); _Pragma("unroll") for (int m = 0; m < 4; ++m) _Pragma("unroll") for (int n = 0; n < 2; ++n) _Pragma("unroll") for (int k = 0; k < 2; ++k) \
;         acc[ai][bj][m][n] = __builtin_amdgcn_mfma_f32_16x16x32_bf16(Bt[n][k], At[m][k], acc[ai][bj][m][n], 0, 0, 0); __builtin_amdgcn_s_setprio(0); } while (0)
; #define PG8_WAIT_V(n) asm volatile("s_waitcnt vmcnt(" #n ")" ::: "memory")
; #define PG8_WAIT_L(n) asm volatile("s_waitcnt lgkmcnt(" #n ")" ::: "memory")
; #define PG8_BAR __builtin_amdgcn_s_barrier()
; #define PG8_SCHED __builtin_amdgcn_sched_barrier(0)
; template <class Epi, class Sched>
; __device__ __forceinline__ void gemm_phase(LAS unsigned char* lds, const Gemm g, const Sched& S, const Epi& E) {
;     ...
;         for (int t = 0; t < nt; t += 2) {
;             const bool last = (t == nt - 2);
;             const char* a1 = cA + (size_t)(t + 1) * kstep;
;             const char* a2 = last ? nA : cA + (size_t)(t + 2) * kstep; const char* b2 = last ? nB : cB + (size_t)(t + 2) * kstep;
;             const char* a3 = a2 + kstep; const char* b3 = b2 + kstep;
;     ...
;             PG8_LDB(B0, 0, 0); PG8_LDB(B1, 0, 1); PG8_SCHED; PG8_LDA(At, 0, 0); PG8_STAGE(PG8_SA(1, 1), a1 + hstepA, voffA);
;             PG8_WAIT_V(8); PG8_WAIT_L(0); PG8_BAR; PG8_MMA(0, 0, At, B0); PG8_MMA(0, 1, At, B1); PG8_BAR; PG8_SCHED;
;             PG8_LDA(At, 0, 1); PG8_STAGE(PG8_SB(0, 0), b2, voffB); PG8_STAGE(PG8_SB(0, 1), b2 + hstepB, voffB); PG8_STAGE(PG8_SA(0, 0), a2, voffA);
;             PG8_WAIT_V(8); PG8_WAIT_L(0); PG8_BAR; PG8_MMA(1, 0, At, B0); PG8_MMA(1, 1, At, B1); PG8_BAR; PG8_SCHED;
.LBB0_98:
	s_add_u32 s4, s22, 0xfff80080
	s_addc_u32 s54, s23, -1
	s_add_i32 s78, 0, 0x10000
	s_cmp_eq_u32 s94, 28
	s_cselect_b32 s57, s27, s54
	s_cselect_b32 s56, s47, s4
	v_add_u32_e32 v172, s78, v165
	s_cselect_b32 s55, s49, s92
	s_cselect_b32 s54, s61, s65
	s_add_i32 s4, 0, 0x14000
	ds_read_b128 v[156:159], v172
	ds_read_b128 v[160:163], v172 offset:1024
	ds_read_b128 v[168:171], v172 offset:2048
	ds_read_b128 v[182:185], v172 offset:3072
	v_add_u32_e32 v172, s4, v165
	ds_read_b128 v[186:189], v172
	ds_read_b128 v[194:197], v172 offset:1024
	ds_read_b128 v[198:201], v172 offset:2048
	ds_read_b128 v[202:205], v172 offset:3072
	v_lshl_add_u64 v[172:173], s[22:23], 0, v[134:135]
	s_add_i32 m0, s30, 0xc000
	ds_read_b128 v[206:209], v167
	ds_read_b128 v[210:213], v167 offset:1024
	ds_read_b128 v[214:217], v167 offset:2048
	ds_read_b128 v[218:221], v167 offset:3072
	ds_read_b128 v[222:225], v167 offset:4096
	ds_read_b128 v[226:229], v167 offset:5120
	ds_read_b128 v[230:233], v167 offset:6144
	ds_read_b128 v[234:237], v167 offset:7168
	global_load_lds_dwordx4 v[172:173], off
	v_lshl_add_u64 v[172:173], s[22:23], 0, v[154:155]
	s_add_i32 m0, s30, 0xe000
	s_nop 0
	global_load_lds_dwordx4 v[172:173], off
	s_waitcnt vmcnt(8)
	s_waitcnt lgkmcnt(0)
	s_barrier
	s_setprio 1
	s_waitcnt lgkmcnt(0)
	v_mfma_f32_16x16x32_bf16 v[124:127], v[156:159], v[206:209], v[124:127]
	v_mfma_f32_16x16x32_bf16 v[120:123], v[168:171], v[206:209], v[120:123]
	v_mfma_f32_16x16x32_bf16 v[108:111], v[156:159], v[214:217], v[108:111]
	v_mfma_f32_16x16x32_bf16 v[104:107], v[168:171], v[214:217], v[104:107]
	v_mfma_f32_16x16x32_bf16 v[92:95], v[156:159], v[222:225], v[92:95]
	v_mfma_f32_16x16x32_bf16 v[88:91], v[168:171], v[222:225], v[88:91]
	v_mfma_f32_16x16x32_bf16 v[76:79], v[156:159], v[230:233], v[76:79]
	v_mfma_f32_16x16x32_bf16 v[72:75], v[168:171], v[230:233], v[72:75]
	s_setprio 0
	s_setprio 1
	v_mfma_f32_16x16x32_bf16 v[124:127], v[160:163], v[210:213], v[124:127]
	v_mfma_f32_16x16x32_bf16 v[120:123], v[182:185], v[210:213], v[120:123]
	v_mfma_f32_16x16x32_bf16 v[108:111], v[160:163], v[218:221], v[108:111]
	v_mfma_f32_16x16x32_bf16 v[104:107], v[182:185], v[218:221], v[104:107]
	v_mfma_f32_16x16x32_bf16 v[92:95], v[160:163], v[226:229], v[92:95]
	v_mfma_f32_16x16x32_bf16 v[88:91], v[182:185], v[226:229], v[88:91]
	v_mfma_f32_16x16x32_bf16 v[76:79], v[160:163], v[234:237], v[76:79]
	v_mfma_f32_16x16x32_bf16 v[72:75], v[182:185], v[234:237], v[72:75]
	s_setprio 0
	s_setprio 1
	v_mfma_f32_16x16x32_bf16 v[116:119], v[186:189], v[206:209], v[116:119]
	v_mfma_f32_16x16x32_bf16 v[112:115], v[198:201], v[206:209], v[112:115]
	v_mfma_f32_16x16x32_bf16 v[100:103], v[186:189], v[214:217], v[100:103]
	v_mfma_f32_16x16x32_bf16 v[96:99], v[198:201], v[214:217], v[96:99]
	v_mfma_f32_16x16x32_bf16 v[84:87], v[186:189], v[222:225], v[84:87]
	v_mfma_f32_16x16x32_bf16 v[80:83], v[198:201], v[222:225], v[80:83]
	v_mfma_f32_16x16x32_bf16 v[68:71], v[186:189], v[230:233], v[68:71]
	v_mfma_f32_16x16x32_bf16 v[64:67], v[198:201], v[230:233], v[64:67]
	s_setprio 0
	s_setprio 1
	v_mfma_f32_16x16x32_bf16 v[116:119], v[194:197], v[210:213], v[116:119]
	v_mfma_f32_16x16x32_bf16 v[112:115], v[202:205], v[210:213], v[112:115]
	v_mfma_f32_16x16x32_bf16 v[100:103], v[194:197], v[218:221], v[100:103]
	v_mfma_f32_16x16x32_bf16 v[96:99], v[202:205], v[218:221], v[96:99]
	v_mfma_f32_16x16x32_bf16 v[84:87], v[194:197], v[226:229], v[84:87]
	v_mfma_f32_16x16x32_bf16 v[80:83], v[202:205], v[226:229], v[80:83]
	v_mfma_f32_16x16x32_bf16 v[68:71], v[194:197], v[234:237], v[68:71]
	v_mfma_f32_16x16x32_bf16 v[64:67], v[202:205], v[234:237], v[64:67]
	s_setprio 0
	s_barrier
	s_add_i32 s78, s78, s28
	v_lshl_add_u64 v[172:173], s[54:55], 0, v[136:137]
	s_mov_b32 m0, s78
	ds_read_b128 v[206:209], v167 offset:16384
	ds_read_b128 v[210:213], v167 offset:17408
	ds_read_b128 v[214:217], v167 offset:18432
	ds_read_b128 v[218:221], v167 offset:19456
	ds_read_b128 v[222:225], v167 offset:20480
	ds_read_b128 v[226:229], v167 offset:21504
	ds_read_b128 v[230:233], v167 offset:22528
	ds_read_b128 v[234:237], v167 offset:23552
	global_load_lds_dwordx4 v[172:173], off
	s_add_i32 m0, s78, 0x2000
	s_add_u32 s78, s54, 0x80000
	v_lshl_add_u64 v[190:191], s[54:55], 0, v[128:129]
	s_addc_u32 s79, s55, 0
	s_add_i32 s4, s4, s28
	global_load_lds_dwordx4 v[190:191], off
	v_lshl_add_u64 v[238:239], s[78:79], 0, v[136:137]
	s_mov_b32 m0, s4
	v_lshl_add_u64 v[240:241], s[56:57], 0, v[130:131]
	global_load_lds_dwordx4 v[238:239], off
	v_lshl_add_u64 v[238:239], s[78:79], 0, v[128:129]
	s_add_i32 m0, s4, 0x2000
	s_nop 0
	global_load_lds_dwordx4 v[238:239], off
	v_lshl_add_u64 v[238:239], s[56:57], 0, v[132:133]
	s_mov_b32 m0, s30
	s_nop 0
	global_load_lds_dwordx4 v[238:239], off
	s_mov_b32 m0, s34
	s_nop 0
	global_load_lds_dwordx4 v[240:241], off
	s_waitcnt vmcnt(8)
	s_waitcnt lgkmcnt(0)
	s_barrier
; #define PG8_STAGE(bufoff, gbase, voff) do { _Pragma("unroll") for (int _i = 0; _i < 2; ++_i) \
;         __builtin_amdgcn_global_load_lds((const unsigned*)((const char*)(gbase) + (voff)[_i]), (LAS unsigned*)(lds + (bufoff) + ldsw + _i * 8192), 16, 0, PG8_AUX); } while (0)
; #define PG8_LDA(dst, b, h) do { _Pragma("unroll") for (int m = 0; m < 4; ++m) _Pragma("unroll") for (int k = 0; k < 2; ++k) dst[m][k] = *(const LAS bf16x8*)(lds + PG8_SA(b, h) + aoff + m * 2048 + k * 1024); } while (0)
; #define PG8_LDB(dst, b, h) do { _Pragma("unroll") for (int n = 0; n < 2; ++n) _Pragma("unroll") for (int k = 0; k < 2; ++k) dst[n][k] = *(const LAS bf16x8*)(lds + PG8_SB(b, h) + boff + n * 2048 + k * 1024); } while (0)
; #define PG8_MMA(ai, bj, At, Bt) do { __builtin_amdgcn_s_setprio(1); _Pragma("unroll") for (int m = 0; m < 4; ++m) _Pragma("unroll") for (int n = 0; n < 2; ++n) _Pragma("unroll") for (int k = 0; k < 2; ++k) \
;         acc[ai][bj][m][n] = __builtin_amdgcn_mfma_f32_16x16x32_bf16(Bt[n][k], At[m][k], acc[ai][bj][m][n], 0, 0, 0); __builtin_amdgcn_s_setprio(0); } while (0)
; #define PG8_WAIT_V(n) asm volatile("s_waitcnt vmcnt(" #n ")" ::: "memory")
; #define PG8_WAIT_L(n) asm volatile("s_waitcnt lgkmcnt(" #n ")" ::: "memory")
; #define PG8_BAR __builtin_amdgcn_s_barrier()
; #define PG8_SCHED __builtin_amdgcn_sched_barrier(0)
; template <class Epi, class Sched>
; __device__ __forceinline__ void gemm_phase(LAS unsigned char* lds, const Gemm g, const Sched& S, const Epi& E) {
;     ...
;             PG8_WAIT_V(8); PG8_WAIT_L(0); PG8_BAR; PG8_MMA(1, 0, At, B0); PG8_MMA(1, 1, At, B1); PG8_BAR; PG8_SCHED;
;             PG8_LDB(B0, 1, 0); PG8_LDB(B1, 1, 1); PG8_SCHED; PG8_LDA(At, 1, 0); PG8_STAGE(PG8_SA(0, 1), a2 + hstepA, voffA);
;             PG8_WAIT_V(8); PG8_WAIT_L(0); PG8_BAR; PG8_MMA(0, 0, At, B0); PG8_MMA(0, 1, At, B1); PG8_BAR; PG8_SCHED;
	s_setprio 1
	s_waitcnt lgkmcnt(0)
	v_mfma_f32_16x16x32_bf16 v[60:63], v[156:159], v[206:209], v[60:63]
	v_mfma_f32_16x16x32_bf16 v[56:59], v[168:171], v[206:209], v[56:59]
	v_mfma_f32_16x16x32_bf16 v[44:47], v[156:159], v[214:217], v[44:47]
	v_mfma_f32_16x16x32_bf16 v[40:43], v[168:171], v[214:217], v[40:43]
	v_mfma_f32_16x16x32_bf16 v[28:31], v[156:159], v[222:225], v[28:31]
	v_mfma_f32_16x16x32_bf16 v[24:27], v[168:171], v[222:225], v[24:27]
	v_mfma_f32_16x16x32_bf16 v[12:15], v[156:159], v[230:233], v[12:15]
	v_mfma_f32_16x16x32_bf16 v[8:11], v[168:171], v[230:233], v[8:11]
	s_setprio 0
	s_setprio 1
	v_mfma_f32_16x16x32_bf16 v[60:63], v[160:163], v[210:213], v[60:63]
	v_mfma_f32_16x16x32_bf16 v[56:59], v[182:185], v[210:213], v[56:59]
	v_mfma_f32_16x16x32_bf16 v[44:47], v[160:163], v[218:221], v[44:47]
	v_mfma_f32_16x16x32_bf16 v[40:43], v[182:185], v[218:221], v[40:43]
	v_mfma_f32_16x16x32_bf16 v[28:31], v[160:163], v[226:229], v[28:31]
	v_mfma_f32_16x16x32_bf16 v[24:27], v[182:185], v[226:229], v[24:27]
	v_mfma_f32_16x16x32_bf16 v[12:15], v[160:163], v[234:237], v[12:15]
	v_mfma_f32_16x16x32_bf16 v[8:11], v[182:185], v[234:237], v[8:11]
	s_setprio 0
	s_setprio 1
	v_mfma_f32_16x16x32_bf16 v[52:55], v[186:189], v[206:209], v[52:55]
	v_mfma_f32_16x16x32_bf16 v[48:51], v[198:201], v[206:209], v[48:51]
	v_mfma_f32_16x16x32_bf16 v[36:39], v[186:189], v[214:217], v[36:39]
	v_mfma_f32_16x16x32_bf16 v[32:35], v[198:201], v[214:217], v[32:35]
	v_mfma_f32_16x16x32_bf16 v[20:23], v[186:189], v[222:225], v[20:23]
	v_mfma_f32_16x16x32_bf16 v[16:19], v[198:201], v[222:225], v[16:19]
	v_mfma_f32_16x16x32_bf16 v[4:7], v[186:189], v[230:233], v[4:7]
	v_mfma_f32_16x16x32_bf16 v[0:3], v[198:201], v[230:233], v[0:3]
	s_setprio 0
	s_setprio 1
	v_mfma_f32_16x16x32_bf16 v[52:55], v[194:197], v[210:213], v[52:55]
	v_mfma_f32_16x16x32_bf16 v[48:51], v[202:205], v[210:213], v[48:51]
	v_mfma_f32_16x16x32_bf16 v[36:39], v[194:197], v[218:221], v[36:39]
	v_mfma_f32_16x16x32_bf16 v[32:35], v[202:205], v[218:221], v[32:35]
	v_mfma_f32_16x16x32_bf16 v[20:23], v[194:197], v[226:229], v[20:23]
	v_mfma_f32_16x16x32_bf16 v[16:19], v[202:205], v[226:229], v[16:19]
	v_mfma_f32_16x16x32_bf16 v[4:7], v[194:197], v[234:237], v[4:7]
	v_mfma_f32_16x16x32_bf16 v[0:3], v[202:205], v[234:237], v[0:3]
	s_setprio 0
	s_barrier
	s_add_i32 s4, 0, 0x18000
	v_add_u32_e32 v181, s4, v165
	s_add_i32 s78, 0, 0x1c000
	ds_read_b128 v[156:159], v181
	ds_read_b128 v[160:163], v181 offset:1024
	ds_read_b128 v[168:171], v181 offset:2048
	ds_read_b128 v[182:185], v181 offset:3072
	v_add_u32_e32 v181, s78, v165
	ds_read_b128 v[186:189], v181
	ds_read_b128 v[194:197], v181 offset:1024
	ds_read_b128 v[198:201], v181 offset:2048
	ds_read_b128 v[202:205], v181 offset:3072
	s_add_u32 s56, s56, 0x80000
	s_addc_u32 s57, s57, 0
	s_mov_b32 m0, s36
	v_lshl_add_u64 v[242:243], s[56:57], 0, v[132:133]
	ds_read_b128 v[206:209], v167 offset:32768
	ds_read_b128 v[210:213], v167 offset:33792
	ds_read_b128 v[214:217], v167 offset:34816
	ds_read_b128 v[218:221], v167 offset:35840
	ds_read_b128 v[222:225], v167 offset:36864
	ds_read_b128 v[226:229], v167 offset:37888
	ds_read_b128 v[230:233], v167 offset:38912
	ds_read_b128 v[234:237], v167 offset:39936
	global_load_lds_dwordx4 v[242:243], off
	v_lshl_add_u64 v[242:243], s[56:57], 0, v[130:131]
	s_mov_b32 m0, s62
	s_nop 0
	global_load_lds_dwordx4 v[242:243], off
	s_waitcnt vmcnt(8)
	s_waitcnt lgkmcnt(0)
	s_barrier
	s_setprio 1
	s_waitcnt lgkmcnt(0)
	v_mfma_f32_16x16x32_bf16 v[124:127], v[156:159], v[206:209], v[124:127]
	v_mfma_f32_16x16x32_bf16 v[120:123], v[168:171], v[206:209], v[120:123]
	v_mfma_f32_16x16x32_bf16 v[108:111], v[156:159], v[214:217], v[108:111]
	v_mfma_f32_16x16x32_bf16 v[104:107], v[168:171], v[214:217], v[104:107]
	v_mfma_f32_16x16x32_bf16 v[92:95], v[156:159], v[222:225], v[92:95]
	v_mfma_f32_16x16x32_bf16 v[88:91], v[168:171], v[222:225], v[88:91]
	v_mfma_f32_16x16x32_bf16 v[76:79], v[156:159], v[230:233], v[76:79]
	v_mfma_f32_16x16x32_bf16 v[72:75], v[168:171], v[230:233], v[72:75]
	s_setprio 0
	s_setprio 1
	v_mfma_f32_16x16x32_bf16 v[124:127], v[160:163], v[210:213], v[124:127]
	v_mfma_f32_16x16x32_bf16 v[120:123], v[182:185], v[210:213], v[120:123]
	v_mfma_f32_16x16x32_bf16 v[108:111], v[160:163], v[218:221], v[108:111]
	v_mfma_f32_16x16x32_bf16 v[104:107], v[182:185], v[218:221], v[104:107]
	v_mfma_f32_16x16x32_bf16 v[92:95], v[160:163], v[226:229], v[92:95]
	v_mfma_f32_16x16x32_bf16 v[88:91], v[182:185], v[226:229], v[88:91]
	v_mfma_f32_16x16x32_bf16 v[76:79], v[160:163], v[234:237], v[76:79]
	v_mfma_f32_16x16x32_bf16 v[72:75], v[182:185], v[234:237], v[72:75]
	s_setprio 0
	s_setprio 1
	v_mfma_f32_16x16x32_bf16 v[116:119], v[186:189], v[206:209], v[116:119]
	v_mfma_f32_16x16x32_bf16 v[112:115], v[198:201], v[206:209], v[112:115]
	v_mfma_f32_16x16x32_bf16 v[100:103], v[186:189], v[214:217], v[100:103]
	v_mfma_f32_16x16x32_bf16 v[96:99], v[198:201], v[214:217], v[96:99]
	v_mfma_f32_16x16x32_bf16 v[84:87], v[186:189], v[222:225], v[84:87]
	v_mfma_f32_16x16x32_bf16 v[80:83], v[198:201], v[222:225], v[80:83]
	v_mfma_f32_16x16x32_bf16 v[68:71], v[186:189], v[230:233], v[68:71]
	v_mfma_f32_16x16x32_bf16 v[64:67], v[198:201], v[230:233], v[64:67]
	s_setprio 0
	s_setprio 1
	v_mfma_f32_16x16x32_bf16 v[116:119], v[194:197], v[210:213], v[116:119]
	v_mfma_f32_16x16x32_bf16 v[112:115], v[202:205], v[210:213], v[112:115]
	v_mfma_f32_16x16x32_bf16 v[100:103], v[194:197], v[218:221], v[100:103]
	v_mfma_f32_16x16x32_bf16 v[96:99], v[202:205], v[218:221], v[96:99]
	v_mfma_f32_16x16x32_bf16 v[84:87], v[194:197], v[226:229], v[84:87]
	v_mfma_f32_16x16x32_bf16 v[80:83], v[202:205], v[226:229], v[80:83]
	v_mfma_f32_16x16x32_bf16 v[68:71], v[194:197], v[234:237], v[68:71]
	v_mfma_f32_16x16x32_bf16 v[64:67], v[202:205], v[234:237], v[64:67]
	s_setprio 0
	s_barrier
; #define PG8_STAGE(bufoff, gbase, voff) do { _Pragma("unroll") for (int _i = 0; _i < 2; ++_i) \
;         __builtin_amdgcn_global_load_lds((const unsigned*)((const char*)(gbase) + (voff)[_i]), (LAS unsigned*)(lds + (bufoff) + ldsw + _i * 8192), 16, 0, PG8_AUX); } while (0)
; #define PG8_LDA(dst, b, h) do { _Pragma("unroll") for (int m = 0; m < 4; ++m) _Pragma("unroll") for (int k = 0; k < 2; ++k) dst[m][k] = *(const LAS bf16x8*)(lds + PG8_SA(b, h) + aoff + m * 2048 + k * 1024); } while (0)
; #define PG8_MMA(ai, bj, At, Bt) do { __builtin_amdgcn_s_setprio(1); _Pragma("unroll") for (int m = 0; m < 4; ++m) _Pragma("unroll") for (int n = 0; n < 2; ++n) _Pragma("unroll") for (int k = 0; k < 2; ++k) \
;         acc[ai][bj][m][n] = __builtin_amdgcn_mfma_f32_16x16x32_bf16(Bt[n][k], At[m][k], acc[ai][bj][m][n], 0, 0, 0); __builtin_amdgcn_s_setprio(0); } while (0)
; #define PG8_WAIT_V(n) asm volatile("s_waitcnt vmcnt(" #n ")" ::: "memory")
; #define PG8_WAIT_L(n) asm volatile("s_waitcnt lgkmcnt(" #n ")" ::: "memory")
; #define PG8_BAR __builtin_amdgcn_s_barrier()
; #define PG8_SCHED __builtin_amdgcn_sched_barrier(0)
; template <class Epi, class Sched>
; __device__ __forceinline__ void gemm_phase(LAS unsigned char* lds, const Gemm g, const Sched& S, const Epi& E) {
;     ...
;             PG8_LDA(At, 1, 1); PG8_STAGE(PG8_SB(1, 0), b3, voffB); PG8_STAGE(PG8_SB(1, 1), b3 + hstepB, voffB); PG8_STAGE(PG8_SA(1, 0), a3, voffA);
;             PG8_WAIT_V(8); PG8_WAIT_L(0); PG8_BAR; PG8_MMA(1, 0, At, B0); PG8_MMA(1, 1, At, B1); PG8_BAR; PG8_SCHED;
	s_add_i32 s4, s4, s28
	v_lshl_add_u64 v[172:173], v[172:173], 0, s[12:13]
	s_mov_b32 m0, s4
	ds_read_b128 v[206:209], v167 offset:49152
	ds_read_b128 v[210:213], v167 offset:50176
	ds_read_b128 v[214:217], v167 offset:51200
	ds_read_b128 v[218:221], v167 offset:52224
	ds_read_b128 v[222:225], v167 offset:53248
	ds_read_b128 v[226:229], v167 offset:54272
	ds_read_b128 v[230:233], v167 offset:55296
	ds_read_b128 v[234:237], v167 offset:56320
	global_load_lds_dwordx4 v[172:173], off
	s_add_i32 m0, s4, 0x2000
	s_add_u32 s54, s54, 0x80080
	v_lshl_add_u64 v[172:173], v[190:191], 0, s[12:13]
	s_addc_u32 s55, s55, 0
	s_add_i32 s4, s78, s28
	global_load_lds_dwordx4 v[172:173], off
	v_lshl_add_u64 v[172:173], s[54:55], 0, v[136:137]
	s_mov_b32 m0, s4
	s_nop 0
	global_load_lds_dwordx4 v[172:173], off
	v_lshl_add_u64 v[172:173], s[54:55], 0, v[128:129]
	s_add_i32 m0, s4, 0x2000
	s_nop 0
	global_load_lds_dwordx4 v[172:173], off
	v_lshl_add_u64 v[172:173], v[238:239], 0, s[12:13]
	s_mov_b32 m0, s63
	s_nop 0
	global_load_lds_dwordx4 v[172:173], off
	v_lshl_add_u64 v[172:173], v[240:241], 0, s[12:13]
	s_mov_b32 m0, s64
	s_nop 0
	global_load_lds_dwordx4 v[172:173], off
	s_waitcnt vmcnt(8)
	s_waitcnt lgkmcnt(0)
	s_barrier
	s_setprio 1
	s_waitcnt lgkmcnt(0)
	v_mfma_f32_16x16x32_bf16 v[60:63], v[156:159], v[206:209], v[60:63]
	v_mfma_f32_16x16x32_bf16 v[56:59], v[168:171], v[206:209], v[56:59]
	v_mfma_f32_16x16x32_bf16 v[44:47], v[156:159], v[214:217], v[44:47]
	v_mfma_f32_16x16x32_bf16 v[40:43], v[168:171], v[214:217], v[40:43]
	v_mfma_f32_16x16x32_bf16 v[28:31], v[156:159], v[222:225], v[28:31]
	v_mfma_f32_16x16x32_bf16 v[24:27], v[168:171], v[222:225], v[24:27]
	v_mfma_f32_16x16x32_bf16 v[12:15], v[156:159], v[230:233], v[12:15]
	v_mfma_f32_16x16x32_bf16 v[8:11], v[168:171], v[230:233], v[8:11]
	s_setprio 0
	s_setprio 1
	v_mfma_f32_16x16x32_bf16 v[60:63], v[160:163], v[210:213], v[60:63]
	v_mfma_f32_16x16x32_bf16 v[56:59], v[182:185], v[210:213], v[56:59]
	v_mfma_f32_16x16x32_bf16 v[44:47], v[160:163], v[218:221], v[44:47]
	v_mfma_f32_16x16x32_bf16 v[40:43], v[182:185], v[218:221], v[40:43]
	v_mfma_f32_16x16x32_bf16 v[28:31], v[160:163], v[226:229], v[28:31]
	v_mfma_f32_16x16x32_bf16 v[24:27], v[182:185], v[226:229], v[24:27]
	v_mfma_f32_16x16x32_bf16 v[12:15], v[160:163], v[234:237], v[12:15]
	v_mfma_f32_16x16x32_bf16 v[8:11], v[182:185], v[234:237], v[8:11]
	s_setprio 0
	s_setprio 1
	v_mfma_f32_16x16x32_bf16 v[52:55], v[186:189], v[206:209], v[52:55]
	v_mfma_f32_16x16x32_bf16 v[48:51], v[198:201], v[206:209], v[48:51]
	v_mfma_f32_16x16x32_bf16 v[36:39], v[186:189], v[214:217], v[36:39]
	v_mfma_f32_16x16x32_bf16 v[32:35], v[198:201], v[214:217], v[32:35]
	v_mfma_f32_16x16x32_bf16 v[20:23], v[186:189], v[222:225], v[20:23]
	v_mfma_f32_16x16x32_bf16 v[16:19], v[198:201], v[222:225], v[16:19]
	v_mfma_f32_16x16x32_bf16 v[4:7], v[186:189], v[230:233], v[4:7]
	v_mfma_f32_16x16x32_bf16 v[0:3], v[198:201], v[230:233], v[0:3]
	s_setprio 0
	s_setprio 1
	v_mfma_f32_16x16x32_bf16 v[52:55], v[194:197], v[210:213], v[52:55]
	v_mfma_f32_16x16x32_bf16 v[48:51], v[202:205], v[210:213], v[48:51]
	v_mfma_f32_16x16x32_bf16 v[36:39], v[194:197], v[218:221], v[36:39]
	v_mfma_f32_16x16x32_bf16 v[32:35], v[202:205], v[218:221], v[32:35]
	v_mfma_f32_16x16x32_bf16 v[20:23], v[194:197], v[226:229], v[20:23]
	v_mfma_f32_16x16x32_bf16 v[16:19], v[202:205], v[226:229], v[16:19]
	v_mfma_f32_16x16x32_bf16 v[4:7], v[194:197], v[234:237], v[4:7]
	v_mfma_f32_16x16x32_bf16 v[0:3], v[202:205], v[234:237], v[0:3]
	s_setprio 0
	s_barrier
	s_add_i32 s94, s94, 2
	s_add_u32 s22, s22, 0x100
	s_addc_u32 s23, s23, 0
	s_add_u32 s65, s65, 0x100
	s_addc_u32 s92, s92, 0
	s_cmp_gt_u32 s94, 29
	s_cbranch_scc0 .LBB0_98
	s_and_b64 vcc, exec, s[44:45]
	s_cbranch_vccz .LBB0_101
	s_barrier

; #define PG8_STAGE(bufoff, gbase, voff) do { _Pragma("unroll") for (int _i = 0; _i < 2; ++_i) \
;         __builtin_amdgcn_global_load_lds((const unsigned*)((const char*)(gbase) + (voff)[_i]), (LAS unsigned*)(lds + (bufoff) + ldsw + _i * 8192), 16, 0, PG8_AUX); } while (0)
; #define PG8_LDA(dst, b, h) do { _Pragma("unroll") for (int m = 0; m < 4; ++m) _Pragma("unroll") for (int k = 0; k < 2; ++k) dst[m][k] = *(const LAS bf16x8*)(lds + PG8_SA(b, h) + aoff + m * 2048 + k * 1024); } while (0)
; #define PG8_LDB(dst, b, h) do { _Pragma("unroll") for (int n = 0; n < 2; ++n) _Pragma("unroll") for (int k = 0; k < 2; ++k) dst[n][k] = *(const LAS bf16x8*)(lds + PG8_SB(b, h) + boff + n * 2048 + k * 1024); } while (0)
; #define PG8_MMA(ai, bj, At, Bt) do { __builtin_amdgcn_s_setprio(1); _Pragma("unroll") for (int m = 0; m < 4; ++m) _Pragma("unroll") for (int n = 0; n < 2; ++n) _Pragma("unroll") for (int k = 0; k < 2; ++k) \
;         acc[ai][bj][m][n] = __builtin_amdgcn_mfma_f32_16x16x32_bf16(Bt[n][k], At[m][k], acc[ai][bj][m][n], 0, 0, 0); __builtin_amdgcn_s_setprio(0); } while (0)
; #define PG8_WAIT_V(n) asm volatile("s_waitcnt vmcnt(" #n ")" ::: "memory")
; #define PG8_WAIT_L(n) asm volatile("s_waitcnt lgkmcnt(" #n ")" ::: "memory")
; #define PG8_BAR __builtin_amdgcn_s_barrier()
; #define PG8_SCHED __builtin_amdgcn_sched_barrier(0)
; template <class Epi, class Sched>
; __device__ __forceinline__ void gemm_phase(LAS unsigned char* lds, const Gemm g, const Sched& S, const Epi& E) {
;     ...
;         for (int t = 0; t < nt; t += 2) {
;             const bool last = (t == nt - 2);
;             const char* a1 = cA + (size_t)(t + 1) * kstep;
;             const char* a2 = last ? nA : cA + (size_t)(t + 2) * kstep; const char* b2 = last ? nB : cB + (size_t)(t + 2) * kstep;
;             const char* a3 = a2 + kstep; const char* b3 = b2 + kstep;
;     ...
;             PG8_LDB(B0, 0, 0); PG8_LDB(B1, 0, 1); PG8_SCHED; PG8_LDA(At, 0, 0); PG8_STAGE(PG8_SA(1, 1), a1 + hstepA, voffA);
;             PG8_WAIT_V(8); PG8_WAIT_L(0); PG8_BAR; PG8_MMA(0, 0, At, B0); PG8_MMA(0, 1, At, B1); PG8_BAR; PG8_SCHED;
;             PG8_LDA(At, 0, 1); PG8_STAGE(PG8_SB(0, 0), b2, voffB); PG8_STAGE(PG8_SB(0, 1), b2 + hstepB, voffB); PG8_STAGE(PG8_SA(0, 0), a2, voffA);
;             PG8_WAIT_V(8); PG8_WAIT_L(0); PG8_BAR; PG8_MMA(1, 0, At, B0); PG8_MMA(1, 1, At, B1); PG8_BAR; PG8_SCHED;
.LBB0_141:
	s_add_i32 s49, s4, 2
	s_add_u32 s40, s22, 0xfff80080
	s_addc_u32 s41, s23, -1
	s_add_i32 s65, 0, 0x10000
	s_cmp_eq_u32 s20, s4
	s_cselect_b32 s53, s1, s41
	s_cselect_b32 s52, s0, s40
	s_cselect_b32 s41, s51, s47
	s_cselect_b32 s40, s50, s27
	s_add_i32 s4, 0, 0x14000
	v_add_u32_e32 v168, s65, v173
	v_add_u32_e32 v183, s4, v173
	ds_read_b128 v[128:131], v168
	ds_read_b128 v[132:135], v168 offset:1024
	ds_read_b128 v[164:167], v168 offset:2048
	ds_read_b128 v[168:171], v168 offset:3072
	ds_read_b128 v[184:187], v183
	ds_read_b128 v[188:191], v183 offset:1024
	ds_read_b128 v[194:197], v183 offset:2048
	ds_read_b128 v[198:201], v183 offset:3072
	v_lshl_add_u64 v[234:235], s[22:23], 0, v[160:161]
	s_add_i32 m0, s30, 0xc000
	ds_read_b128 v[202:205], v182
	ds_read_b128 v[206:209], v182 offset:1024
	ds_read_b128 v[210:213], v182 offset:2048
	ds_read_b128 v[214:217], v182 offset:3072
	ds_read_b128 v[218:221], v182 offset:4096
	ds_read_b128 v[222:225], v182 offset:5120
	ds_read_b128 v[226:229], v182 offset:6144
	ds_read_b128 v[230:233], v182 offset:7168
	global_load_lds_dwordx4 v[234:235], off
	v_lshl_add_u64 v[234:235], s[22:23], 0, v[162:163]
	s_add_i32 m0, s30, 0xe000
	s_nop 0
	global_load_lds_dwordx4 v[234:235], off
	s_waitcnt vmcnt(8)
	s_waitcnt lgkmcnt(0)
	s_barrier
	s_setprio 1
	s_waitcnt lgkmcnt(0)
	v_mfma_f32_16x16x32_bf16 v[124:127], v[128:131], v[202:205], v[124:127]
	v_mfma_f32_16x16x32_bf16 v[120:123], v[164:167], v[202:205], v[120:123]
	v_mfma_f32_16x16x32_bf16 v[108:111], v[128:131], v[210:213], v[108:111]
	v_mfma_f32_16x16x32_bf16 v[104:107], v[164:167], v[210:213], v[104:107]
	v_mfma_f32_16x16x32_bf16 v[92:95], v[128:131], v[218:221], v[92:95]
	v_mfma_f32_16x16x32_bf16 v[88:91], v[164:167], v[218:221], v[88:91]
	v_mfma_f32_16x16x32_bf16 v[76:79], v[128:131], v[226:229], v[76:79]
	v_mfma_f32_16x16x32_bf16 v[72:75], v[164:167], v[226:229], v[72:75]
	s_setprio 0
	s_setprio 1
	v_mfma_f32_16x16x32_bf16 v[124:127], v[132:135], v[206:209], v[124:127]
	v_mfma_f32_16x16x32_bf16 v[120:123], v[168:171], v[206:209], v[120:123]
	v_mfma_f32_16x16x32_bf16 v[108:111], v[132:135], v[214:217], v[108:111]
	v_mfma_f32_16x16x32_bf16 v[104:107], v[168:171], v[214:217], v[104:107]
	v_mfma_f32_16x16x32_bf16 v[92:95], v[132:135], v[222:225], v[92:95]
	v_mfma_f32_16x16x32_bf16 v[88:91], v[168:171], v[222:225], v[88:91]
	v_mfma_f32_16x16x32_bf16 v[76:79], v[132:135], v[230:233], v[76:79]
	v_mfma_f32_16x16x32_bf16 v[72:75], v[168:171], v[230:233], v[72:75]
	s_setprio 0
	s_setprio 1
	v_mfma_f32_16x16x32_bf16 v[116:119], v[184:187], v[202:205], v[116:119]
	v_mfma_f32_16x16x32_bf16 v[112:115], v[194:197], v[202:205], v[112:115]
	v_mfma_f32_16x16x32_bf16 v[100:103], v[184:187], v[210:213], v[100:103]
	v_mfma_f32_16x16x32_bf16 v[96:99], v[194:197], v[210:213], v[96:99]
	v_mfma_f32_16x16x32_bf16 v[84:87], v[184:187], v[218:221], v[84:87]
	v_mfma_f32_16x16x32_bf16 v[80:83], v[194:197], v[218:221], v[80:83]
	v_mfma_f32_16x16x32_bf16 v[68:71], v[184:187], v[226:229], v[68:71]
	v_mfma_f32_16x16x32_bf16 v[64:67], v[194:197], v[226:229], v[64:67]
	s_setprio 0
	s_setprio 1
	v_mfma_f32_16x16x32_bf16 v[116:119], v[188:191], v[206:209], v[116:119]
	v_mfma_f32_16x16x32_bf16 v[112:115], v[198:201], v[206:209], v[112:115]
	v_mfma_f32_16x16x32_bf16 v[100:103], v[188:191], v[214:217], v[100:103]
	v_mfma_f32_16x16x32_bf16 v[96:99], v[198:201], v[214:217], v[96:99]
	v_mfma_f32_16x16x32_bf16 v[84:87], v[188:191], v[222:225], v[84:87]
	v_mfma_f32_16x16x32_bf16 v[80:83], v[198:201], v[222:225], v[80:83]
	v_mfma_f32_16x16x32_bf16 v[68:71], v[188:191], v[230:233], v[68:71]
	v_mfma_f32_16x16x32_bf16 v[64:67], v[198:201], v[230:233], v[64:67]
	s_setprio 0
	s_barrier
	s_add_i32 s65, s65, s28
	v_lshl_add_u64 v[234:235], s[40:41], 0, v[136:137]
	s_mov_b32 m0, s65
	ds_read_b128 v[202:205], v182 offset:16384
	ds_read_b128 v[206:209], v182 offset:17408
	ds_read_b128 v[210:213], v182 offset:18432
	ds_read_b128 v[214:217], v182 offset:19456
	ds_read_b128 v[218:221], v182 offset:20480
	ds_read_b128 v[222:225], v182 offset:21504
	ds_read_b128 v[226:229], v182 offset:22528
	ds_read_b128 v[230:233], v182 offset:23552
	global_load_lds_dwordx4 v[234:235], off
	s_add_i32 m0, s65, 0x2000
	s_add_u32 s78, s40, 0x80000
	v_lshl_add_u64 v[236:237], s[40:41], 0, v[154:155]
	s_addc_u32 s79, s41, 0
	s_add_i32 s4, s4, s28
	global_load_lds_dwordx4 v[236:237], off
	v_lshl_add_u64 v[238:239], s[78:79], 0, v[136:137]
	s_mov_b32 m0, s4
	v_lshl_add_u64 v[240:241], s[52:53], 0, v[156:157]
	global_load_lds_dwordx4 v[238:239], off
	v_lshl_add_u64 v[238:239], s[78:79], 0, v[154:155]
	s_add_i32 m0, s4, 0x2000
	s_nop 0
	global_load_lds_dwordx4 v[238:239], off
	v_lshl_add_u64 v[238:239], s[52:53], 0, v[158:159]
	s_mov_b32 m0, s30
	s_nop 0
	global_load_lds_dwordx4 v[238:239], off
	s_mov_b32 m0, s34
	s_nop 0
	global_load_lds_dwordx4 v[240:241], off
	s_waitcnt vmcnt(8)
	s_waitcnt lgkmcnt(0)
	s_barrier
; #define PG8_STAGE(bufoff, gbase, voff) do { _Pragma("unroll") for (int _i = 0; _i < 2; ++_i) \
;         __builtin_amdgcn_global_load_lds((const unsigned*)((const char*)(gbase) + (voff)[_i]), (LAS unsigned*)(lds + (bufoff) + ldsw + _i * 8192), 16, 0, PG8_AUX); } while (0)
; #define PG8_LDA(dst, b, h) do { _Pragma("unroll") for (int m = 0; m < 4; ++m) _Pragma("unroll") for (int k = 0; k < 2; ++k) dst[m][k] = *(const LAS bf16x8*)(lds + PG8_SA(b, h) + aoff + m * 2048 + k * 1024); } while (0)
; #define PG8_LDB(dst, b, h) do { _Pragma("unroll") for (int n = 0; n < 2; ++n) _Pragma("unroll") for (int k = 0; k < 2; ++k) dst[n][k] = *(const LAS bf16x8*)(lds + PG8_SB(b, h) + boff + n * 2048 + k * 1024); } while (0)
; #define PG8_MMA(ai, bj, At, Bt) do { __builtin_amdgcn_s_setprio(1); _Pragma("unroll") for (int m = 0; m < 4; ++m) _Pragma("unroll") for (int n = 0; n < 2; ++n) _Pragma("unroll") for (int k = 0; k < 2; ++k) \
;         acc[ai][bj][m][n] = __builtin_amdgcn_mfma_f32_16x16x32_bf16(Bt[n][k], At[m][k], acc[ai][bj][m][n], 0, 0, 0); __builtin_amdgcn_s_setprio(0); } while (0)
; #define PG8_WAIT_V(n) asm volatile("s_waitcnt vmcnt(" #n ")" ::: "memory")
; #define PG8_WAIT_L(n) asm volatile("s_waitcnt lgkmcnt(" #n ")" ::: "memory")
; #define PG8_BAR __builtin_amdgcn_s_barrier()
; #define PG8_SCHED __builtin_amdgcn_sched_barrier(0)
; template <class Epi, class Sched>
; __device__ __forceinline__ void gemm_phase(LAS unsigned char* lds, const Gemm g, const Sched& S, const Epi& E) {
;     ...
;             PG8_WAIT_V(8); PG8_WAIT_L(0); PG8_BAR; PG8_MMA(1, 0, At, B0); PG8_MMA(1, 1, At, B1); PG8_BAR; PG8_SCHED;
;             PG8_LDB(B0, 1, 0); PG8_LDB(B1, 1, 1); PG8_SCHED; PG8_LDA(At, 1, 0); PG8_STAGE(PG8_SA(0, 1), a2 + hstepA, voffA);
;             PG8_WAIT_V(8); PG8_WAIT_L(0); PG8_BAR; PG8_MMA(0, 0, At, B0); PG8_MMA(0, 1, At, B1); PG8_BAR; PG8_SCHED;
	s_setprio 1
	s_waitcnt lgkmcnt(0)
	v_mfma_f32_16x16x32_bf16 v[60:63], v[128:131], v[202:205], v[60:63]
	v_mfma_f32_16x16x32_bf16 v[56:59], v[164:167], v[202:205], v[56:59]
	v_mfma_f32_16x16x32_bf16 v[44:47], v[128:131], v[210:213], v[44:47]
	v_mfma_f32_16x16x32_bf16 v[40:43], v[164:167], v[210:213], v[40:43]
	v_mfma_f32_16x16x32_bf16 v[28:31], v[128:131], v[218:221], v[28:31]
	v_mfma_f32_16x16x32_bf16 v[24:27], v[164:167], v[218:221], v[24:27]
	v_mfma_f32_16x16x32_bf16 v[12:15], v[128:131], v[226:229], v[12:15]
	v_mfma_f32_16x16x32_bf16 v[8:11], v[164:167], v[226:229], v[8:11]
	s_setprio 0
	s_setprio 1
	v_mfma_f32_16x16x32_bf16 v[60:63], v[132:135], v[206:209], v[60:63]
	v_mfma_f32_16x16x32_bf16 v[56:59], v[168:171], v[206:209], v[56:59]
	v_mfma_f32_16x16x32_bf16 v[44:47], v[132:135], v[214:217], v[44:47]
	v_mfma_f32_16x16x32_bf16 v[40:43], v[168:171], v[214:217], v[40:43]
	v_mfma_f32_16x16x32_bf16 v[28:31], v[132:135], v[222:225], v[28:31]
	v_mfma_f32_16x16x32_bf16 v[24:27], v[168:171], v[222:225], v[24:27]
	v_mfma_f32_16x16x32_bf16 v[12:15], v[132:135], v[230:233], v[12:15]
	v_mfma_f32_16x16x32_bf16 v[8:11], v[168:171], v[230:233], v[8:11]
	s_setprio 0
	s_setprio 1
	v_mfma_f32_16x16x32_bf16 v[52:55], v[184:187], v[202:205], v[52:55]
	v_mfma_f32_16x16x32_bf16 v[48:51], v[194:197], v[202:205], v[48:51]
	v_mfma_f32_16x16x32_bf16 v[36:39], v[184:187], v[210:213], v[36:39]
	v_mfma_f32_16x16x32_bf16 v[32:35], v[194:197], v[210:213], v[32:35]
	v_mfma_f32_16x16x32_bf16 v[20:23], v[184:187], v[218:221], v[20:23]
	v_mfma_f32_16x16x32_bf16 v[16:19], v[194:197], v[218:221], v[16:19]
	v_mfma_f32_16x16x32_bf16 v[4:7], v[184:187], v[226:229], v[4:7]
	v_mfma_f32_16x16x32_bf16 v[0:3], v[194:197], v[226:229], v[0:3]
	s_setprio 0
	s_setprio 1
	v_mfma_f32_16x16x32_bf16 v[52:55], v[188:191], v[206:209], v[52:55]
	v_mfma_f32_16x16x32_bf16 v[48:51], v[198:201], v[206:209], v[48:51]
	v_mfma_f32_16x16x32_bf16 v[36:39], v[188:191], v[214:217], v[36:39]
	v_mfma_f32_16x16x32_bf16 v[32:35], v[198:201], v[214:217], v[32:35]
	v_mfma_f32_16x16x32_bf16 v[20:23], v[188:191], v[222:225], v[20:23]
	v_mfma_f32_16x16x32_bf16 v[16:19], v[198:201], v[222:225], v[16:19]
	v_mfma_f32_16x16x32_bf16 v[4:7], v[188:191], v[230:233], v[4:7]
	v_mfma_f32_16x16x32_bf16 v[0:3], v[198:201], v[230:233], v[0:3]
	s_setprio 0
	s_barrier
	s_add_i32 s4, 0, 0x18000
	s_add_i32 s65, 0, 0x1c000
	v_add_u32_e32 v168, s4, v173
	v_add_u32_e32 v183, s65, v173
	ds_read_b128 v[128:131], v168
	ds_read_b128 v[132:135], v168 offset:1024
	ds_read_b128 v[164:167], v168 offset:2048
	ds_read_b128 v[168:171], v168 offset:3072
	ds_read_b128 v[184:187], v183
	ds_read_b128 v[188:191], v183 offset:1024
	ds_read_b128 v[194:197], v183 offset:2048
	ds_read_b128 v[198:201], v183 offset:3072
	s_add_u32 s52, s52, 0x80000
	s_addc_u32 s53, s53, 0
	s_mov_b32 m0, s36
	v_lshl_add_u64 v[242:243], s[52:53], 0, v[158:159]
	ds_read_b128 v[202:205], v182 offset:32768
	ds_read_b128 v[206:209], v182 offset:33792
	ds_read_b128 v[210:213], v182 offset:34816
	ds_read_b128 v[214:217], v182 offset:35840
	ds_read_b128 v[218:221], v182 offset:36864
	ds_read_b128 v[222:225], v182 offset:37888
	ds_read_b128 v[226:229], v182 offset:38912
	ds_read_b128 v[230:233], v182 offset:39936
	global_load_lds_dwordx4 v[242:243], off
	v_lshl_add_u64 v[242:243], s[52:53], 0, v[156:157]
	s_mov_b32 m0, s54
	s_nop 0
	global_load_lds_dwordx4 v[242:243], off
	s_waitcnt vmcnt(8)
	s_waitcnt lgkmcnt(0)
	s_barrier
	s_setprio 1
	s_waitcnt lgkmcnt(0)
	v_mfma_f32_16x16x32_bf16 v[124:127], v[128:131], v[202:205], v[124:127]
	v_mfma_f32_16x16x32_bf16 v[120:123], v[164:167], v[202:205], v[120:123]
	v_mfma_f32_16x16x32_bf16 v[108:111], v[128:131], v[210:213], v[108:111]
	v_mfma_f32_16x16x32_bf16 v[104:107], v[164:167], v[210:213], v[104:107]
	v_mfma_f32_16x16x32_bf16 v[92:95], v[128:131], v[218:221], v[92:95]
	v_mfma_f32_16x16x32_bf16 v[88:91], v[164:167], v[218:221], v[88:91]
	v_mfma_f32_16x16x32_bf16 v[76:79], v[128:131], v[226:229], v[76:79]
	v_mfma_f32_16x16x32_bf16 v[72:75], v[164:167], v[226:229], v[72:75]
	s_setprio 0
	s_setprio 1
	v_mfma_f32_16x16x32_bf16 v[124:127], v[132:135], v[206:209], v[124:127]
	v_mfma_f32_16x16x32_bf16 v[120:123], v[168:171], v[206:209], v[120:123]
	v_mfma_f32_16x16x32_bf16 v[108:111], v[132:135], v[214:217], v[108:111]
	v_mfma_f32_16x16x32_bf16 v[104:107], v[168:171], v[214:217], v[104:107]
	v_mfma_f32_16x16x32_bf16 v[92:95], v[132:135], v[222:225], v[92:95]
	v_mfma_f32_16x16x32_bf16 v[88:91], v[168:171], v[222:225], v[88:91]
	v_mfma_f32_16x16x32_bf16 v[76:79], v[132:135], v[230:233], v[76:79]
	v_mfma_f32_16x16x32_bf16 v[72:75], v[168:171], v[230:233], v[72:75]
	s_setprio 0
	s_setprio 1
	v_mfma_f32_16x16x32_bf16 v[116:119], v[184:187], v[202:205], v[116:119]
	v_mfma_f32_16x16x32_bf16 v[112:115], v[194:197], v[202:205], v[112:115]
	v_mfma_f32_16x16x32_bf16 v[100:103], v[184:187], v[210:213], v[100:103]
	v_mfma_f32_16x16x32_bf16 v[96:99], v[194:197], v[210:213], v[96:99]
	v_mfma_f32_16x16x32_bf16 v[84:87], v[184:187], v[218:221], v[84:87]
	v_mfma_f32_16x16x32_bf16 v[80:83], v[194:197], v[218:221], v[80:83]
	v_mfma_f32_16x16x32_bf16 v[68:71], v[184:187], v[226:229], v[68:71]
	v_mfma_f32_16x16x32_bf16 v[64:67], v[194:197], v[226:229], v[64:67]
	s_setprio 0
	s_setprio 1
	v_mfma_f32_16x16x32_bf16 v[116:119], v[188:191], v[206:209], v[116:119]
	v_mfma_f32_16x16x32_bf16 v[112:115], v[198:201], v[206:209], v[112:115]
	v_mfma_f32_16x16x32_bf16 v[100:103], v[188:191], v[214:217], v[100:103]
	v_mfma_f32_16x16x32_bf16 v[96:99], v[198:201], v[214:217], v[96:99]
	v_mfma_f32_16x16x32_bf16 v[84:87], v[188:191], v[222:225], v[84:87]
	v_mfma_f32_16x16x32_bf16 v[80:83], v[198:201], v[222:225], v[80:83]
	v_mfma_f32_16x16x32_bf16 v[68:71], v[188:191], v[230:233], v[68:71]
	v_mfma_f32_16x16x32_bf16 v[64:67], v[198:201], v[230:233], v[64:67]
	s_setprio 0
	s_barrier
; #define PG8_STAGE(bufoff, gbase, voff) do { _Pragma("unroll") for (int _i = 0; _i < 2; ++_i) \
;         __builtin_amdgcn_global_load_lds((const unsigned*)((const char*)(gbase) + (voff)[_i]), (LAS unsigned*)(lds + (bufoff) + ldsw + _i * 8192), 16, 0, PG8_AUX); } while (0)
; #define PG8_LDA(dst, b, h) do { _Pragma("unroll") for (int m = 0; m < 4; ++m) _Pragma("unroll") for (int k = 0; k < 2; ++k) dst[m][k] = *(const LAS bf16x8*)(lds + PG8_SA(b, h) + aoff + m * 2048 + k * 1024); } while (0)
; #define PG8_MMA(ai, bj, At, Bt) do { __builtin_amdgcn_s_setprio(1); _Pragma("unroll") for (int m = 0; m < 4; ++m) _Pragma("unroll") for (int n = 0; n < 2; ++n) _Pragma("unroll") for (int k = 0; k < 2; ++k) \
;         acc[ai][bj][m][n] = __builtin_amdgcn_mfma_f32_16x16x32_bf16(Bt[n][k], At[m][k], acc[ai][bj][m][n], 0, 0, 0); __builtin_amdgcn_s_setprio(0); } while (0)
; #define PG8_WAIT_V(n) asm volatile("s_waitcnt vmcnt(" #n ")" ::: "memory")
; #define PG8_WAIT_L(n) asm volatile("s_waitcnt lgkmcnt(" #n ")" ::: "memory")
; #define PG8_BAR __builtin_amdgcn_s_barrier()
; #define PG8_SCHED __builtin_amdgcn_sched_barrier(0)
; template <class Epi, class Sched>
; __device__ __forceinline__ void gemm_phase(LAS unsigned char* lds, const Gemm g, const Sched& S, const Epi& E) {
;     ...
;             PG8_LDA(At, 1, 1); PG8_STAGE(PG8_SB(1, 0), b3, voffB); PG8_STAGE(PG8_SB(1, 1), b3 + hstepB, voffB); PG8_STAGE(PG8_SA(1, 0), a3, voffA);
;             PG8_WAIT_V(8); PG8_WAIT_L(0); PG8_BAR; PG8_MMA(1, 0, At, B0); PG8_MMA(1, 1, At, B1); PG8_BAR; PG8_SCHED;
	s_add_i32 s4, s4, s28
	v_lshl_add_u64 v[234:235], v[234:235], 0, s[12:13]
	s_mov_b32 m0, s4
	ds_read_b128 v[202:205], v182 offset:49152
	ds_read_b128 v[206:209], v182 offset:50176
	ds_read_b128 v[210:213], v182 offset:51200
	ds_read_b128 v[214:217], v182 offset:52224
	ds_read_b128 v[218:221], v182 offset:53248
	ds_read_b128 v[222:225], v182 offset:54272
	ds_read_b128 v[226:229], v182 offset:55296
	ds_read_b128 v[230:233], v182 offset:56320
	global_load_lds_dwordx4 v[234:235], off
	s_add_i32 m0, s4, 0x2000
	s_add_u32 s40, s40, 0x80080
	v_lshl_add_u64 v[234:235], v[236:237], 0, s[12:13]
	s_addc_u32 s41, s41, 0
	s_add_i32 s4, s65, s28
	global_load_lds_dwordx4 v[234:235], off
	v_lshl_add_u64 v[234:235], s[40:41], 0, v[136:137]
	s_mov_b32 m0, s4
	s_nop 0
	global_load_lds_dwordx4 v[234:235], off
	v_lshl_add_u64 v[234:235], s[40:41], 0, v[154:155]
	s_add_i32 m0, s4, 0x2000
	s_nop 0
	global_load_lds_dwordx4 v[234:235], off
	v_lshl_add_u64 v[234:235], v[238:239], 0, s[12:13]
	s_mov_b32 m0, s55
	s_nop 0
	global_load_lds_dwordx4 v[234:235], off
	v_lshl_add_u64 v[234:235], v[240:241], 0, s[12:13]
	s_mov_b32 m0, s56
	s_nop 0
	global_load_lds_dwordx4 v[234:235], off
	s_waitcnt vmcnt(8)
	s_waitcnt lgkmcnt(0)
	s_barrier
	s_setprio 1
	s_waitcnt lgkmcnt(0)
	v_mfma_f32_16x16x32_bf16 v[60:63], v[128:131], v[202:205], v[60:63]
	v_mfma_f32_16x16x32_bf16 v[56:59], v[164:167], v[202:205], v[56:59]
	v_mfma_f32_16x16x32_bf16 v[44:47], v[128:131], v[210:213], v[44:47]
	v_mfma_f32_16x16x32_bf16 v[40:43], v[164:167], v[210:213], v[40:43]
	v_mfma_f32_16x16x32_bf16 v[28:31], v[128:131], v[218:221], v[28:31]
	v_mfma_f32_16x16x32_bf16 v[24:27], v[164:167], v[218:221], v[24:27]
	v_mfma_f32_16x16x32_bf16 v[12:15], v[128:131], v[226:229], v[12:15]
	v_mfma_f32_16x16x32_bf16 v[8:11], v[164:167], v[226:229], v[8:11]
	s_setprio 0
	s_setprio 1
	v_mfma_f32_16x16x32_bf16 v[60:63], v[132:135], v[206:209], v[60:63]
	v_mfma_f32_16x16x32_bf16 v[56:59], v[168:171], v[206:209], v[56:59]
	v_mfma_f32_16x16x32_bf16 v[44:47], v[132:135], v[214:217], v[44:47]
	v_mfma_f32_16x16x32_bf16 v[40:43], v[168:171], v[214:217], v[40:43]
	v_mfma_f32_16x16x32_bf16 v[28:31], v[132:135], v[222:225], v[28:31]
	v_mfma_f32_16x16x32_bf16 v[24:27], v[168:171], v[222:225], v[24:27]
	v_mfma_f32_16x16x32_bf16 v[12:15], v[132:135], v[230:233], v[12:15]
	v_mfma_f32_16x16x32_bf16 v[8:11], v[168:171], v[230:233], v[8:11]
	s_setprio 0
	s_setprio 1
	v_mfma_f32_16x16x32_bf16 v[52:55], v[184:187], v[202:205], v[52:55]
	v_mfma_f32_16x16x32_bf16 v[48:51], v[194:197], v[202:205], v[48:51]
	v_mfma_f32_16x16x32_bf16 v[36:39], v[184:187], v[210:213], v[36:39]
	v_mfma_f32_16x16x32_bf16 v[32:35], v[194:197], v[210:213], v[32:35]
	v_mfma_f32_16x16x32_bf16 v[20:23], v[184:187], v[218:221], v[20:23]
	v_mfma_f32_16x16x32_bf16 v[16:19], v[194:197], v[218:221], v[16:19]
	v_mfma_f32_16x16x32_bf16 v[4:7], v[184:187], v[226:229], v[4:7]
	v_mfma_f32_16x16x32_bf16 v[0:3], v[194:197], v[226:229], v[0:3]
	s_setprio 0
	s_setprio 1
	v_mfma_f32_16x16x32_bf16 v[52:55], v[188:191], v[206:209], v[52:55]
	v_mfma_f32_16x16x32_bf16 v[48:51], v[198:201], v[206:209], v[48:51]
	v_mfma_f32_16x16x32_bf16 v[36:39], v[188:191], v[214:217], v[36:39]
	v_mfma_f32_16x16x32_bf16 v[32:35], v[198:201], v[214:217], v[32:35]
	v_mfma_f32_16x16x32_bf16 v[20:23], v[188:191], v[222:225], v[20:23]
	v_mfma_f32_16x16x32_bf16 v[16:19], v[198:201], v[222:225], v[16:19]
	v_mfma_f32_16x16x32_bf16 v[4:7], v[188:191], v[230:233], v[4:7]
	v_mfma_f32_16x16x32_bf16 v[0:3], v[198:201], v[230:233], v[0:3]
	s_setprio 0
	s_barrier
	s_add_u32 s22, s22, 0x100
	s_addc_u32 s23, s23, 0
	s_add_u32 s27, s27, 0x100
	s_addc_u32 s47, s47, 0
	s_cmp_ge_u32 s49, s61
	s_mov_b32 s4, s49
	s_cbranch_scc0 .LBB0_141
	s_and_b64 vcc, exec, s[44:45]
	s_cbranch_vccz .LBB0_144
	s_barrier

; #define PG8_STAGE(bufoff, gbase, voff) do { _Pragma("unroll") for (int _i = 0; _i < 2; ++_i) \
;         __builtin_amdgcn_global_load_lds((const unsigned*)((const char*)(gbase) + (voff)[_i]), (LAS unsigned*)(lds + (bufoff) + ldsw + _i * 8192), 16, 0, PG8_AUX); } while (0)
; #define PG8_LDA(dst, b, h) do { _Pragma("unroll") for (int m = 0; m < 4; ++m) _Pragma("unroll") for (int k = 0; k < 2; ++k) dst[m][k] = *(const LAS bf16x8*)(lds + PG8_SA(b, h) + aoff + m * 2048 + k * 1024); } while (0)
; #define PG8_LDB(dst, b, h) do { _Pragma("unroll") for (int n = 0; n < 2; ++n) _Pragma("unroll") for (int k = 0; k < 2; ++k) dst[n][k] = *(const LAS bf16x8*)(lds + PG8_SB(b, h) + boff + n * 2048 + k * 1024); } while (0)
; #define PG8_MMA(ai, bj, At, Bt) do { __builtin_amdgcn_s_setprio(1); _Pragma("unroll") for (int m = 0; m < 4; ++m) _Pragma("unroll") for (int n = 0; n < 2; ++n) _Pragma("unroll") for (int k = 0; k < 2; ++k) \
;         acc[ai][bj][m][n] = __builtin_amdgcn_mfma_f32_16x16x32_bf16(Bt[n][k], At[m][k], acc[ai][bj][m][n], 0, 0, 0); __builtin_amdgcn_s_setprio(0); } while (0)
; #define PG8_WAIT_V(n) asm volatile("s_waitcnt vmcnt(" #n ")" ::: "memory")
; #define PG8_WAIT_L(n) asm volatile("s_waitcnt lgkmcnt(" #n ")" ::: "memory")
; #define PG8_BAR __builtin_amdgcn_s_barrier()
; #define PG8_SCHED __builtin_amdgcn_sched_barrier(0)
; template <class Epi, class Sched>
; __device__ __forceinline__ void gemm_phase(LAS unsigned char* lds, const Gemm g, const Sched& S, const Epi& E) {
;     ...
;         for (int t = 0; t < nt; t += 2) {
;             const bool last = (t == nt - 2);
;             const char* a1 = cA + (size_t)(t + 1) * kstep;
;             const char* a2 = last ? nA : cA + (size_t)(t + 2) * kstep; const char* b2 = last ? nB : cB + (size_t)(t + 2) * kstep;
;             const char* a3 = a2 + kstep; const char* b3 = b2 + kstep;
;     ...
;             PG8_LDB(B0, 0, 0); PG8_LDB(B1, 0, 1); PG8_SCHED; PG8_LDA(At, 0, 0); PG8_STAGE(PG8_SA(1, 1), a1 + hstepA, voffA);
;             PG8_WAIT_V(8); PG8_WAIT_L(0); PG8_BAR; PG8_MMA(0, 0, At, B0); PG8_MMA(0, 1, At, B1); PG8_BAR; PG8_SCHED;
;             PG8_LDA(At, 0, 1); PG8_STAGE(PG8_SB(0, 0), b2, voffB); PG8_STAGE(PG8_SB(0, 1), b2 + hstepB, voffB); PG8_STAGE(PG8_SA(0, 0), a2, voffA);
;             PG8_WAIT_V(8); PG8_WAIT_L(0); PG8_BAR; PG8_MMA(1, 0, At, B0); PG8_MMA(1, 1, At, B1); PG8_BAR; PG8_SCHED;
.LBB0_197:
	s_add_u32 s4, s48, 0xfffe0080
	s_addc_u32 s50, s49, -1
	s_add_i32 s64, 0, 0x10000
	s_cmp_eq_u32 s63, 4
	s_cselect_b32 s53, s27, s50
	s_cselect_b32 s52, s41, s4
	v_add_u32_e32 v172, s64, v161
	s_cselect_b32 s51, s43, s62
	s_cselect_b32 s50, s60, s61
	s_add_i32 s4, 0, 0x14000
	ds_read_b128 v[156:159], v172
	ds_read_b128 v[164:167], v172 offset:1024
	ds_read_b128 v[168:171], v172 offset:2048
	ds_read_b128 v[182:185], v172 offset:3072
	v_add_u32_e32 v172, s4, v161
	ds_read_b128 v[186:189], v172
	ds_read_b128 v[194:197], v172 offset:1024
	ds_read_b128 v[198:201], v172 offset:2048
	ds_read_b128 v[202:205], v172 offset:3072
	v_lshl_add_u64 v[172:173], s[48:49], 0, v[134:135]
	s_add_i32 m0, s30, 0xc000
	ds_read_b128 v[206:209], v163
	ds_read_b128 v[210:213], v163 offset:1024
	ds_read_b128 v[214:217], v163 offset:2048
	ds_read_b128 v[218:221], v163 offset:3072
	ds_read_b128 v[222:225], v163 offset:4096
	ds_read_b128 v[226:229], v163 offset:5120
	ds_read_b128 v[230:233], v163 offset:6144
	ds_read_b128 v[234:237], v163 offset:7168
	global_load_lds_dwordx4 v[172:173], off
	v_lshl_add_u64 v[172:173], s[48:49], 0, v[154:155]
	s_add_i32 m0, s30, 0xe000
	s_nop 0
	global_load_lds_dwordx4 v[172:173], off
	s_waitcnt vmcnt(8)
	s_waitcnt lgkmcnt(0)
	s_barrier
	s_setprio 1
	s_waitcnt lgkmcnt(0)
	v_mfma_f32_16x16x32_bf16 v[124:127], v[156:159], v[206:209], v[124:127]
	v_mfma_f32_16x16x32_bf16 v[120:123], v[168:171], v[206:209], v[120:123]
	v_mfma_f32_16x16x32_bf16 v[108:111], v[156:159], v[214:217], v[108:111]
	v_mfma_f32_16x16x32_bf16 v[104:107], v[168:171], v[214:217], v[104:107]
	v_mfma_f32_16x16x32_bf16 v[96:99], v[156:159], v[222:225], v[96:99]
	v_mfma_f32_16x16x32_bf16 v[88:91], v[168:171], v[222:225], v[88:91]
	v_mfma_f32_16x16x32_bf16 v[76:79], v[156:159], v[230:233], v[76:79]
	v_mfma_f32_16x16x32_bf16 v[72:75], v[168:171], v[230:233], v[72:75]
	s_setprio 0
	s_setprio 1
	v_mfma_f32_16x16x32_bf16 v[124:127], v[164:167], v[210:213], v[124:127]
	v_mfma_f32_16x16x32_bf16 v[120:123], v[182:185], v[210:213], v[120:123]
	v_mfma_f32_16x16x32_bf16 v[108:111], v[164:167], v[218:221], v[108:111]
	v_mfma_f32_16x16x32_bf16 v[104:107], v[182:185], v[218:221], v[104:107]
	v_mfma_f32_16x16x32_bf16 v[96:99], v[164:167], v[226:229], v[96:99]
	v_mfma_f32_16x16x32_bf16 v[88:91], v[182:185], v[226:229], v[88:91]
	v_mfma_f32_16x16x32_bf16 v[76:79], v[164:167], v[234:237], v[76:79]
	v_mfma_f32_16x16x32_bf16 v[72:75], v[182:185], v[234:237], v[72:75]
	s_setprio 0
	s_setprio 1
	v_mfma_f32_16x16x32_bf16 v[116:119], v[186:189], v[206:209], v[116:119]
	v_mfma_f32_16x16x32_bf16 v[112:115], v[198:201], v[206:209], v[112:115]
	v_mfma_f32_16x16x32_bf16 v[100:103], v[186:189], v[214:217], v[100:103]
	v_mfma_f32_16x16x32_bf16 v[92:95], v[198:201], v[214:217], v[92:95]
	v_mfma_f32_16x16x32_bf16 v[84:87], v[186:189], v[222:225], v[84:87]
	v_mfma_f32_16x16x32_bf16 v[80:83], v[198:201], v[222:225], v[80:83]
	v_mfma_f32_16x16x32_bf16 v[68:71], v[186:189], v[230:233], v[68:71]
	v_mfma_f32_16x16x32_bf16 v[64:67], v[198:201], v[230:233], v[64:67]
	s_setprio 0
	s_setprio 1
	v_mfma_f32_16x16x32_bf16 v[116:119], v[194:197], v[210:213], v[116:119]
	v_mfma_f32_16x16x32_bf16 v[112:115], v[202:205], v[210:213], v[112:115]
	v_mfma_f32_16x16x32_bf16 v[100:103], v[194:197], v[218:221], v[100:103]
	v_mfma_f32_16x16x32_bf16 v[92:95], v[202:205], v[218:221], v[92:95]
	v_mfma_f32_16x16x32_bf16 v[84:87], v[194:197], v[226:229], v[84:87]
	v_mfma_f32_16x16x32_bf16 v[80:83], v[202:205], v[226:229], v[80:83]
	v_mfma_f32_16x16x32_bf16 v[68:71], v[194:197], v[234:237], v[68:71]
	v_mfma_f32_16x16x32_bf16 v[64:67], v[202:205], v[234:237], v[64:67]
	s_setprio 0
	s_barrier
	s_add_i32 s64, s64, s28
	v_lshl_add_u64 v[172:173], s[50:51], 0, v[136:137]
	s_mov_b32 m0, s64
	ds_read_b128 v[206:209], v163 offset:16384
	ds_read_b128 v[210:213], v163 offset:17408
	ds_read_b128 v[214:217], v163 offset:18432
	ds_read_b128 v[218:221], v163 offset:19456
	ds_read_b128 v[222:225], v163 offset:20480
	ds_read_b128 v[226:229], v163 offset:21504
	ds_read_b128 v[230:233], v163 offset:22528
	ds_read_b128 v[234:237], v163 offset:23552
	global_load_lds_dwordx4 v[172:173], off
	s_add_i32 m0, s64, 0x2000
	s_add_u32 s64, s50, 0x20000
	v_lshl_add_u64 v[190:191], s[50:51], 0, v[128:129]
	s_addc_u32 s65, s51, 0
	s_add_i32 s4, s4, s28
	global_load_lds_dwordx4 v[190:191], off
	v_lshl_add_u64 v[238:239], s[64:65], 0, v[136:137]
	s_mov_b32 m0, s4
	v_lshl_add_u64 v[240:241], s[52:53], 0, v[130:131]
	global_load_lds_dwordx4 v[238:239], off
	v_lshl_add_u64 v[238:239], s[64:65], 0, v[128:129]
	s_add_i32 m0, s4, 0x2000
	s_nop 0
	global_load_lds_dwordx4 v[238:239], off
	v_lshl_add_u64 v[238:239], s[52:53], 0, v[132:133]
	s_mov_b32 m0, s30
	s_nop 0
	global_load_lds_dwordx4 v[238:239], off
	s_mov_b32 m0, s34
	s_nop 0
	global_load_lds_dwordx4 v[240:241], off
	s_waitcnt vmcnt(8)
	s_waitcnt lgkmcnt(0)
	s_barrier
; #define PG8_STAGE(bufoff, gbase, voff) do { _Pragma("unroll") for (int _i = 0; _i < 2; ++_i) \
;         __builtin_amdgcn_global_load_lds((const unsigned*)((const char*)(gbase) + (voff)[_i]), (LAS unsigned*)(lds + (bufoff) + ldsw + _i * 8192), 16, 0, PG8_AUX); } while (0)
; #define PG8_LDA(dst, b, h) do { _Pragma("unroll") for (int m = 0; m < 4; ++m) _Pragma("unroll") for (int k = 0; k < 2; ++k) dst[m][k] = *(const LAS bf16x8*)(lds + PG8_SA(b, h) + aoff + m * 2048 + k * 1024); } while (0)
; #define PG8_LDB(dst, b, h) do { _Pragma("unroll") for (int n = 0; n < 2; ++n) _Pragma("unroll") for (int k = 0; k < 2; ++k) dst[n][k] = *(const LAS bf16x8*)(lds + PG8_SB(b, h) + boff + n * 2048 + k * 1024); } while (0)
; #define PG8_MMA(ai, bj, At, Bt) do { __builtin_amdgcn_s_setprio(1); _Pragma("unroll") for (int m = 0; m < 4; ++m) _Pragma("unroll") for (int n = 0; n < 2; ++n) _Pragma("unroll") for (int k = 0; k < 2; ++k) \
;         acc[ai][bj][m][n] = __builtin_amdgcn_mfma_f32_16x16x32_bf16(Bt[n][k], At[m][k], acc[ai][bj][m][n], 0, 0, 0); __builtin_amdgcn_s_setprio(0); } while (0)
; #define PG8_WAIT_V(n) asm volatile("s_waitcnt vmcnt(" #n ")" ::: "memory")
; #define PG8_WAIT_L(n) asm volatile("s_waitcnt lgkmcnt(" #n ")" ::: "memory")
; #define PG8_BAR __builtin_amdgcn_s_barrier()
; #define PG8_SCHED __builtin_amdgcn_sched_barrier(0)
; template <class Epi, class Sched>
; __device__ __forceinline__ void gemm_phase(LAS unsigned char* lds, const Gemm g, const Sched& S, const Epi& E) {
;     ...
;             PG8_WAIT_V(8); PG8_WAIT_L(0); PG8_BAR; PG8_MMA(1, 0, At, B0); PG8_MMA(1, 1, At, B1); PG8_BAR; PG8_SCHED;
;             PG8_LDB(B0, 1, 0); PG8_LDB(B1, 1, 1); PG8_SCHED; PG8_LDA(At, 1, 0); PG8_STAGE(PG8_SA(0, 1), a2 + hstepA, voffA);
;             PG8_WAIT_V(8); PG8_WAIT_L(0); PG8_BAR; PG8_MMA(0, 0, At, B0); PG8_MMA(0, 1, At, B1); PG8_BAR; PG8_SCHED;
	s_setprio 1
	s_waitcnt lgkmcnt(0)
	v_mfma_f32_16x16x32_bf16 v[60:63], v[156:159], v[206:209], v[60:63]
	v_mfma_f32_16x16x32_bf16 v[56:59], v[168:171], v[206:209], v[56:59]
	v_mfma_f32_16x16x32_bf16 v[44:47], v[156:159], v[214:217], v[44:47]
	v_mfma_f32_16x16x32_bf16 v[40:43], v[168:171], v[214:217], v[40:43]
	v_mfma_f32_16x16x32_bf16 v[28:31], v[156:159], v[222:225], v[28:31]
	v_mfma_f32_16x16x32_bf16 v[24:27], v[168:171], v[222:225], v[24:27]
	v_mfma_f32_16x16x32_bf16 v[12:15], v[156:159], v[230:233], v[12:15]
	v_mfma_f32_16x16x32_bf16 v[8:11], v[168:171], v[230:233], v[8:11]
	s_setprio 0
	s_setprio 1
	v_mfma_f32_16x16x32_bf16 v[60:63], v[164:167], v[210:213], v[60:63]
	v_mfma_f32_16x16x32_bf16 v[56:59], v[182:185], v[210:213], v[56:59]
	v_mfma_f32_16x16x32_bf16 v[44:47], v[164:167], v[218:221], v[44:47]
	v_mfma_f32_16x16x32_bf16 v[40:43], v[182:185], v[218:221], v[40:43]
	v_mfma_f32_16x16x32_bf16 v[28:31], v[164:167], v[226:229], v[28:31]
	v_mfma_f32_16x16x32_bf16 v[24:27], v[182:185], v[226:229], v[24:27]
	v_mfma_f32_16x16x32_bf16 v[12:15], v[164:167], v[234:237], v[12:15]
	v_mfma_f32_16x16x32_bf16 v[8:11], v[182:185], v[234:237], v[8:11]
	s_setprio 0
	s_setprio 1
	v_mfma_f32_16x16x32_bf16 v[52:55], v[186:189], v[206:209], v[52:55]
	v_mfma_f32_16x16x32_bf16 v[48:51], v[198:201], v[206:209], v[48:51]
	v_mfma_f32_16x16x32_bf16 v[36:39], v[186:189], v[214:217], v[36:39]
	v_mfma_f32_16x16x32_bf16 v[32:35], v[198:201], v[214:217], v[32:35]
	v_mfma_f32_16x16x32_bf16 v[20:23], v[186:189], v[222:225], v[20:23]
	v_mfma_f32_16x16x32_bf16 v[16:19], v[198:201], v[222:225], v[16:19]
	v_mfma_f32_16x16x32_bf16 v[4:7], v[186:189], v[230:233], v[4:7]
	v_mfma_f32_16x16x32_bf16 v[0:3], v[198:201], v[230:233], v[0:3]
	s_setprio 0
	s_setprio 1
	v_mfma_f32_16x16x32_bf16 v[52:55], v[194:197], v[210:213], v[52:55]
	v_mfma_f32_16x16x32_bf16 v[48:51], v[202:205], v[210:213], v[48:51]
	v_mfma_f32_16x16x32_bf16 v[36:39], v[194:197], v[218:221], v[36:39]
	v_mfma_f32_16x16x32_bf16 v[32:35], v[202:205], v[218:221], v[32:35]
	v_mfma_f32_16x16x32_bf16 v[20:23], v[194:197], v[226:229], v[20:23]
	v_mfma_f32_16x16x32_bf16 v[16:19], v[202:205], v[226:229], v[16:19]
	v_mfma_f32_16x16x32_bf16 v[4:7], v[194:197], v[234:237], v[4:7]
	v_mfma_f32_16x16x32_bf16 v[0:3], v[202:205], v[234:237], v[0:3]
	s_setprio 0
	s_barrier
	s_add_i32 s4, 0, 0x18000
	v_add_u32_e32 v181, s4, v161
	s_add_i32 s64, 0, 0x1c000
	ds_read_b128 v[156:159], v181
	ds_read_b128 v[164:167], v181 offset:1024
	ds_read_b128 v[168:171], v181 offset:2048
	ds_read_b128 v[182:185], v181 offset:3072
	v_add_u32_e32 v181, s64, v161
	ds_read_b128 v[186:189], v181
	ds_read_b128 v[194:197], v181 offset:1024
	ds_read_b128 v[198:201], v181 offset:2048
	ds_read_b128 v[202:205], v181 offset:3072
	s_add_u32 s52, s52, 0x20000
	s_addc_u32 s53, s53, 0
	s_mov_b32 m0, s36
	v_lshl_add_u64 v[242:243], s[52:53], 0, v[132:133]
	ds_read_b128 v[206:209], v163 offset:32768
	ds_read_b128 v[210:213], v163 offset:33792
	ds_read_b128 v[214:217], v163 offset:34816
	ds_read_b128 v[218:221], v163 offset:35840
	ds_read_b128 v[222:225], v163 offset:36864
	ds_read_b128 v[226:229], v163 offset:37888
	ds_read_b128 v[230:233], v163 offset:38912
	ds_read_b128 v[234:237], v163 offset:39936
	global_load_lds_dwordx4 v[242:243], off
	v_lshl_add_u64 v[242:243], s[52:53], 0, v[130:131]
	s_mov_b32 m0, s54
	s_nop 0
	global_load_lds_dwordx4 v[242:243], off
	s_waitcnt vmcnt(8)
	s_waitcnt lgkmcnt(0)
	s_barrier
	s_setprio 1
	s_waitcnt lgkmcnt(0)
	v_mfma_f32_16x16x32_bf16 v[124:127], v[156:159], v[206:209], v[124:127]
	v_mfma_f32_16x16x32_bf16 v[120:123], v[168:171], v[206:209], v[120:123]
	v_mfma_f32_16x16x32_bf16 v[108:111], v[156:159], v[214:217], v[108:111]
	v_mfma_f32_16x16x32_bf16 v[104:107], v[168:171], v[214:217], v[104:107]
	v_mfma_f32_16x16x32_bf16 v[96:99], v[156:159], v[222:225], v[96:99]
	v_mfma_f32_16x16x32_bf16 v[88:91], v[168:171], v[222:225], v[88:91]
	v_mfma_f32_16x16x32_bf16 v[76:79], v[156:159], v[230:233], v[76:79]
	v_mfma_f32_16x16x32_bf16 v[72:75], v[168:171], v[230:233], v[72:75]
	s_setprio 0
	s_setprio 1
	v_mfma_f32_16x16x32_bf16 v[124:127], v[164:167], v[210:213], v[124:127]
	v_mfma_f32_16x16x32_bf16 v[120:123], v[182:185], v[210:213], v[120:123]
	v_mfma_f32_16x16x32_bf16 v[108:111], v[164:167], v[218:221], v[108:111]
	v_mfma_f32_16x16x32_bf16 v[104:107], v[182:185], v[218:221], v[104:107]
	v_mfma_f32_16x16x32_bf16 v[96:99], v[164:167], v[226:229], v[96:99]
	v_mfma_f32_16x16x32_bf16 v[88:91], v[182:185], v[226:229], v[88:91]
	v_mfma_f32_16x16x32_bf16 v[76:79], v[164:167], v[234:237], v[76:79]
	v_mfma_f32_16x16x32_bf16 v[72:75], v[182:185], v[234:237], v[72:75]
	s_setprio 0
	s_setprio 1
	v_mfma_f32_16x16x32_bf16 v[116:119], v[186:189], v[206:209], v[116:119]
	v_mfma_f32_16x16x32_bf16 v[112:115], v[198:201], v[206:209], v[112:115]
	v_mfma_f32_16x16x32_bf16 v[100:103], v[186:189], v[214:217], v[100:103]
	v_mfma_f32_16x16x32_bf16 v[92:95], v[198:201], v[214:217], v[92:95]
	v_mfma_f32_16x16x32_bf16 v[84:87], v[186:189], v[222:225], v[84:87]
	v_mfma_f32_16x16x32_bf16 v[80:83], v[198:201], v[222:225], v[80:83]
	v_mfma_f32_16x16x32_bf16 v[68:71], v[186:189], v[230:233], v[68:71]
	v_mfma_f32_16x16x32_bf16 v[64:67], v[198:201], v[230:233], v[64:67]
	s_setprio 0
	s_setprio 1
	v_mfma_f32_16x16x32_bf16 v[116:119], v[194:197], v[210:213], v[116:119]
	v_mfma_f32_16x16x32_bf16 v[112:115], v[202:205], v[210:213], v[112:115]
	v_mfma_f32_16x16x32_bf16 v[100:103], v[194:197], v[218:221], v[100:103]
	v_mfma_f32_16x16x32_bf16 v[92:95], v[202:205], v[218:221], v[92:95]
	v_mfma_f32_16x16x32_bf16 v[84:87], v[194:197], v[226:229], v[84:87]
	v_mfma_f32_16x16x32_bf16 v[80:83], v[202:205], v[226:229], v[80:83]
	v_mfma_f32_16x16x32_bf16 v[68:71], v[194:197], v[234:237], v[68:71]
	v_mfma_f32_16x16x32_bf16 v[64:67], v[202:205], v[234:237], v[64:67]
	s_setprio 0
	s_barrier
; #define PG8_STAGE(bufoff, gbase, voff) do { _Pragma("unroll") for (int _i = 0; _i < 2; ++_i) \
;         __builtin_amdgcn_global_load_lds((const unsigned*)((const char*)(gbase) + (voff)[_i]), (LAS unsigned*)(lds + (bufoff) + ldsw + _i * 8192), 16, 0, PG8_AUX); } while (0)
; #define PG8_LDA(dst, b, h) do { _Pragma("unroll") for (int m = 0; m < 4; ++m) _Pragma("unroll") for (int k = 0; k < 2; ++k) dst[m][k] = *(const LAS bf16x8*)(lds + PG8_SA(b, h) + aoff + m * 2048 + k * 1024); } while (0)
; #define PG8_MMA(ai, bj, At, Bt) do { __builtin_amdgcn_s_setprio(1); _Pragma("unroll") for (int m = 0; m < 4; ++m) _Pragma("unroll") for (int n = 0; n < 2; ++n) _Pragma("unroll") for (int k = 0; k < 2; ++k) \
;         acc[ai][bj][m][n] = __builtin_amdgcn_mfma_f32_16x16x32_bf16(Bt[n][k], At[m][k], acc[ai][bj][m][n], 0, 0, 0); __builtin_amdgcn_s_setprio(0); } while (0)
; #define PG8_WAIT_V(n) asm volatile("s_waitcnt vmcnt(" #n ")" ::: "memory")
; #define PG8_WAIT_L(n) asm volatile("s_waitcnt lgkmcnt(" #n ")" ::: "memory")
; #define PG8_BAR __builtin_amdgcn_s_barrier()
; #define PG8_SCHED __builtin_amdgcn_sched_barrier(0)
; template <class Epi, class Sched>
; __device__ __forceinline__ void gemm_phase(LAS unsigned char* lds, const Gemm g, const Sched& S, const Epi& E) {
;     ...
;             PG8_LDA(At, 1, 1); PG8_STAGE(PG8_SB(1, 0), b3, voffB); PG8_STAGE(PG8_SB(1, 1), b3 + hstepB, voffB); PG8_STAGE(PG8_SA(1, 0), a3, voffA);
;             PG8_WAIT_V(8); PG8_WAIT_L(0); PG8_BAR; PG8_MMA(1, 0, At, B0); PG8_MMA(1, 1, At, B1); PG8_BAR; PG8_SCHED;
	s_add_i32 s4, s4, s28
	v_lshl_add_u64 v[172:173], v[172:173], 0, s[12:13]
	s_mov_b32 m0, s4
	ds_read_b128 v[206:209], v163 offset:49152
	ds_read_b128 v[210:213], v163 offset:50176
	ds_read_b128 v[214:217], v163 offset:51200
	ds_read_b128 v[218:221], v163 offset:52224
	ds_read_b128 v[222:225], v163 offset:53248
	ds_read_b128 v[226:229], v163 offset:54272
	ds_read_b128 v[230:233], v163 offset:55296
	ds_read_b128 v[234:237], v163 offset:56320
	global_load_lds_dwordx4 v[172:173], off
	s_add_i32 m0, s4, 0x2000
	s_add_u32 s50, s50, 0x20080
	v_lshl_add_u64 v[172:173], v[190:191], 0, s[12:13]
	s_addc_u32 s51, s51, 0
	s_add_i32 s4, s64, s28
	global_load_lds_dwordx4 v[172:173], off
	v_lshl_add_u64 v[172:173], s[50:51], 0, v[136:137]
	s_mov_b32 m0, s4
	s_nop 0
	global_load_lds_dwordx4 v[172:173], off
	v_lshl_add_u64 v[172:173], s[50:51], 0, v[128:129]
	s_add_i32 m0, s4, 0x2000
	s_nop 0
	global_load_lds_dwordx4 v[172:173], off
	v_lshl_add_u64 v[172:173], v[238:239], 0, s[12:13]
	s_mov_b32 m0, s55
	s_nop 0
	global_load_lds_dwordx4 v[172:173], off
	v_lshl_add_u64 v[172:173], v[240:241], 0, s[12:13]
	s_mov_b32 m0, s56
	s_nop 0
	global_load_lds_dwordx4 v[172:173], off
	s_waitcnt vmcnt(8)
	s_waitcnt lgkmcnt(0)
	s_barrier
	s_setprio 1
	s_waitcnt lgkmcnt(0)
	v_mfma_f32_16x16x32_bf16 v[60:63], v[156:159], v[206:209], v[60:63]
	v_mfma_f32_16x16x32_bf16 v[56:59], v[168:171], v[206:209], v[56:59]
	v_mfma_f32_16x16x32_bf16 v[44:47], v[156:159], v[214:217], v[44:47]
	v_mfma_f32_16x16x32_bf16 v[40:43], v[168:171], v[214:217], v[40:43]
	v_mfma_f32_16x16x32_bf16 v[28:31], v[156:159], v[222:225], v[28:31]
	v_mfma_f32_16x16x32_bf16 v[24:27], v[168:171], v[222:225], v[24:27]
	v_mfma_f32_16x16x32_bf16 v[12:15], v[156:159], v[230:233], v[12:15]
	v_mfma_f32_16x16x32_bf16 v[8:11], v[168:171], v[230:233], v[8:11]
	s_setprio 0
	s_setprio 1
	v_mfma_f32_16x16x32_bf16 v[60:63], v[164:167], v[210:213], v[60:63]
	v_mfma_f32_16x16x32_bf16 v[56:59], v[182:185], v[210:213], v[56:59]
	v_mfma_f32_16x16x32_bf16 v[44:47], v[164:167], v[218:221], v[44:47]
	v_mfma_f32_16x16x32_bf16 v[40:43], v[182:185], v[218:221], v[40:43]
	v_mfma_f32_16x16x32_bf16 v[28:31], v[164:167], v[226:229], v[28:31]
	v_mfma_f32_16x16x32_bf16 v[24:27], v[182:185], v[226:229], v[24:27]
	v_mfma_f32_16x16x32_bf16 v[12:15], v[164:167], v[234:237], v[12:15]
	v_mfma_f32_16x16x32_bf16 v[8:11], v[182:185], v[234:237], v[8:11]
	s_setprio 0
	s_setprio 1
	v_mfma_f32_16x16x32_bf16 v[52:55], v[186:189], v[206:209], v[52:55]
	v_mfma_f32_16x16x32_bf16 v[48:51], v[198:201], v[206:209], v[48:51]
	v_mfma_f32_16x16x32_bf16 v[36:39], v[186:189], v[214:217], v[36:39]
	v_mfma_f32_16x16x32_bf16 v[32:35], v[198:201], v[214:217], v[32:35]
	v_mfma_f32_16x16x32_bf16 v[20:23], v[186:189], v[222:225], v[20:23]
	v_mfma_f32_16x16x32_bf16 v[16:19], v[198:201], v[222:225], v[16:19]
	v_mfma_f32_16x16x32_bf16 v[4:7], v[186:189], v[230:233], v[4:7]
	v_mfma_f32_16x16x32_bf16 v[0:3], v[198:201], v[230:233], v[0:3]
	s_setprio 0
	s_setprio 1
	v_mfma_f32_16x16x32_bf16 v[52:55], v[194:197], v[210:213], v[52:55]
	v_mfma_f32_16x16x32_bf16 v[48:51], v[202:205], v[210:213], v[48:51]
	v_mfma_f32_16x16x32_bf16 v[36:39], v[194:197], v[218:221], v[36:39]
	v_mfma_f32_16x16x32_bf16 v[32:35], v[202:205], v[218:221], v[32:35]
	v_mfma_f32_16x16x32_bf16 v[20:23], v[194:197], v[226:229], v[20:23]
	v_mfma_f32_16x16x32_bf16 v[16:19], v[202:205], v[226:229], v[16:19]
	v_mfma_f32_16x16x32_bf16 v[4:7], v[194:197], v[234:237], v[4:7]
	v_mfma_f32_16x16x32_bf16 v[0:3], v[202:205], v[234:237], v[0:3]
	s_setprio 0
	s_barrier
	s_add_i32 s63, s63, 2
	s_add_u32 s48, s48, 0x100
	s_addc_u32 s49, s49, 0
	s_add_u32 s61, s61, 0x100
	s_addc_u32 s62, s62, 0
	s_cmp_gt_u32 s63, 5
	s_cbranch_scc0 .LBB0_197
	s_and_b64 vcc, exec, s[22:23]
	s_cbranch_vccz .LBB0_200
	s_barrier

; #define PG8_STAGE(bufoff, gbase, voff) do { _Pragma("unroll") for (int _i = 0; _i < 2; ++_i) \
;         __builtin_amdgcn_global_load_lds((const unsigned*)((const char*)(gbase) + (voff)[_i]), (LAS unsigned*)(lds + (bufoff) + ldsw + _i * 8192), 16, 0, PG8_AUX); } while (0)
; #define PG8_LDA(dst, b, h) do { _Pragma("unroll") for (int m = 0; m < 4; ++m) _Pragma("unroll") for (int k = 0; k < 2; ++k) dst[m][k] = *(const LAS bf16x8*)(lds + PG8_SA(b, h) + aoff + m * 2048 + k * 1024); } while (0)
; #define PG8_LDB(dst, b, h) do { _Pragma("unroll") for (int n = 0; n < 2; ++n) _Pragma("unroll") for (int k = 0; k < 2; ++k) dst[n][k] = *(const LAS bf16x8*)(lds + PG8_SB(b, h) + boff + n * 2048 + k * 1024); } while (0)
; #define PG8_MMA(ai, bj, At, Bt) do { __builtin_amdgcn_s_setprio(1); _Pragma("unroll") for (int m = 0; m < 4; ++m) _Pragma("unroll") for (int n = 0; n < 2; ++n) _Pragma("unroll") for (int k = 0; k < 2; ++k) \
;         acc[ai][bj][m][n] = __builtin_amdgcn_mfma_f32_16x16x32_bf16(Bt[n][k], At[m][k], acc[ai][bj][m][n], 0, 0, 0); __builtin_amdgcn_s_setprio(0); } while (0)
; #define PG8_WAIT_V(n) asm volatile("s_waitcnt vmcnt(" #n ")" ::: "memory")
; #define PG8_WAIT_L(n) asm volatile("s_waitcnt lgkmcnt(" #n ")" ::: "memory")
; #define PG8_BAR __builtin_amdgcn_s_barrier()
; #define PG8_SCHED __builtin_amdgcn_sched_barrier(0)
; template <class Epi, class Sched>
; __device__ __forceinline__ void gemm_phase(LAS unsigned char* lds, const Gemm g, const Sched& S, const Epi& E) {
;     ...
;         for (int t = 0; t < nt; t += 2) {
;             const bool last = (t == nt - 2);
;             const char* a1 = cA + (size_t)(t + 1) * kstep;
;             const char* a2 = last ? nA : cA + (size_t)(t + 2) * kstep; const char* b2 = last ? nB : cB + (size_t)(t + 2) * kstep;
;             const char* a3 = a2 + kstep; const char* b3 = b2 + kstep;
;     ...
;             PG8_LDB(B0, 0, 0); PG8_LDB(B1, 0, 1); PG8_SCHED; PG8_LDA(At, 0, 0); PG8_STAGE(PG8_SA(1, 1), a1 + hstepA, voffA);
;             PG8_WAIT_V(8); PG8_WAIT_L(0); PG8_BAR; PG8_MMA(0, 0, At, B0); PG8_MMA(0, 1, At, B1); PG8_BAR; PG8_SCHED;
;             PG8_LDA(At, 0, 1); PG8_STAGE(PG8_SB(0, 0), b2, voffB); PG8_STAGE(PG8_SB(0, 1), b2 + hstepB, voffB); PG8_STAGE(PG8_SA(0, 0), a2, voffA);
;             PG8_WAIT_V(8); PG8_WAIT_L(0); PG8_BAR; PG8_MMA(1, 0, At, B0); PG8_MMA(1, 1, At, B1); PG8_BAR; PG8_SCHED;
.LBB0_382:
	s_add_u32 s4, s0, 0xfff80080
	s_addc_u32 s22, s1, -1
	s_add_i32 s78, 0, 0x10000
	s_cmp_eq_u32 s65, 28
	s_cselect_b32 s41, s20, s22
	s_cselect_b32 s40, s27, s4
	v_add_u32_e32 v136, s78, v182
	s_cselect_b32 s23, s49, s64
	s_cselect_b32 s22, s51, s63
	s_add_i32 s4, 0, 0x14000
	ds_read_b128 v[160:163], v136
	ds_read_b128 v[164:167], v136 offset:1024
	ds_read_b128 v[168:171], v136 offset:2048
	ds_read_b128 v[186:189], v136 offset:3072
	v_add_u32_e32 v136, s4, v182
	ds_read_b128 v[194:197], v136
	ds_read_b128 v[198:201], v136 offset:1024
	ds_read_b128 v[202:205], v136 offset:2048
	ds_read_b128 v[206:209], v136 offset:3072
	v_lshl_add_u64 v[172:173], s[0:1], 0, v[156:157]
	s_add_i32 m0, s30, 0xc000
	ds_read_b128 v[210:213], v184
	ds_read_b128 v[214:217], v184 offset:1024
	ds_read_b128 v[218:221], v184 offset:2048
	ds_read_b128 v[222:225], v184 offset:3072
	ds_read_b128 v[226:229], v184 offset:4096
	ds_read_b128 v[230:233], v184 offset:5120
	ds_read_b128 v[234:237], v184 offset:6144
	ds_read_b128 v[238:241], v184 offset:7168
	global_load_lds_dwordx4 v[172:173], off
	v_lshl_add_u64 v[172:173], s[0:1], 0, v[158:159]
	s_add_i32 m0, s30, 0xe000
	s_nop 0
	global_load_lds_dwordx4 v[172:173], off
	s_waitcnt vmcnt(8)
	s_waitcnt lgkmcnt(0)
	s_barrier
	s_setprio 1
	s_waitcnt lgkmcnt(0)
	v_mfma_f32_16x16x32_bf16 v[124:127], v[160:163], v[210:213], v[124:127]
	v_mfma_f32_16x16x32_bf16 v[120:123], v[168:171], v[210:213], v[120:123]
	v_mfma_f32_16x16x32_bf16 v[108:111], v[160:163], v[218:221], v[108:111]
	v_mfma_f32_16x16x32_bf16 v[104:107], v[168:171], v[218:221], v[104:107]
	v_mfma_f32_16x16x32_bf16 v[92:95], v[160:163], v[226:229], v[92:95]
	v_mfma_f32_16x16x32_bf16 v[88:91], v[168:171], v[226:229], v[88:91]
	v_mfma_f32_16x16x32_bf16 v[76:79], v[160:163], v[234:237], v[76:79]
	v_mfma_f32_16x16x32_bf16 v[72:75], v[168:171], v[234:237], v[72:75]
	s_setprio 0
	s_setprio 1
	v_mfma_f32_16x16x32_bf16 v[124:127], v[164:167], v[214:217], v[124:127]
	v_mfma_f32_16x16x32_bf16 v[120:123], v[186:189], v[214:217], v[120:123]
	v_mfma_f32_16x16x32_bf16 v[108:111], v[164:167], v[222:225], v[108:111]
	v_mfma_f32_16x16x32_bf16 v[104:107], v[186:189], v[222:225], v[104:107]
	v_mfma_f32_16x16x32_bf16 v[92:95], v[164:167], v[230:233], v[92:95]
	v_mfma_f32_16x16x32_bf16 v[88:91], v[186:189], v[230:233], v[88:91]
	v_mfma_f32_16x16x32_bf16 v[76:79], v[164:167], v[238:241], v[76:79]
	v_mfma_f32_16x16x32_bf16 v[72:75], v[186:189], v[238:241], v[72:75]
	s_setprio 0
	s_setprio 1
	v_mfma_f32_16x16x32_bf16 v[116:119], v[194:197], v[210:213], v[116:119]
	v_mfma_f32_16x16x32_bf16 v[112:115], v[202:205], v[210:213], v[112:115]
	v_mfma_f32_16x16x32_bf16 v[100:103], v[194:197], v[218:221], v[100:103]
	v_mfma_f32_16x16x32_bf16 v[96:99], v[202:205], v[218:221], v[96:99]
	v_mfma_f32_16x16x32_bf16 v[84:87], v[194:197], v[226:229], v[84:87]
	v_mfma_f32_16x16x32_bf16 v[80:83], v[202:205], v[226:229], v[80:83]
	v_mfma_f32_16x16x32_bf16 v[68:71], v[194:197], v[234:237], v[68:71]
	v_mfma_f32_16x16x32_bf16 v[64:67], v[202:205], v[234:237], v[64:67]
	s_setprio 0
	s_setprio 1
	v_mfma_f32_16x16x32_bf16 v[116:119], v[198:201], v[214:217], v[116:119]
	v_mfma_f32_16x16x32_bf16 v[112:115], v[206:209], v[214:217], v[112:115]
	v_mfma_f32_16x16x32_bf16 v[100:103], v[198:201], v[222:225], v[100:103]
	v_mfma_f32_16x16x32_bf16 v[96:99], v[206:209], v[222:225], v[96:99]
	v_mfma_f32_16x16x32_bf16 v[84:87], v[198:201], v[230:233], v[84:87]
	v_mfma_f32_16x16x32_bf16 v[80:83], v[206:209], v[230:233], v[80:83]
	v_mfma_f32_16x16x32_bf16 v[68:71], v[198:201], v[238:241], v[68:71]
	v_mfma_f32_16x16x32_bf16 v[64:67], v[206:209], v[238:241], v[64:67]
	s_setprio 0
	s_barrier
	s_add_i32 s78, s78, s28
	v_lshl_add_u64 v[172:173], s[22:23], 0, v[132:133]
	s_mov_b32 m0, s78
	ds_read_b128 v[210:213], v184 offset:16384
	ds_read_b128 v[214:217], v184 offset:17408
	ds_read_b128 v[218:221], v184 offset:18432
	ds_read_b128 v[222:225], v184 offset:19456
	ds_read_b128 v[226:229], v184 offset:20480
	ds_read_b128 v[230:233], v184 offset:21504
	ds_read_b128 v[234:237], v184 offset:22528
	ds_read_b128 v[238:241], v184 offset:23552
	global_load_lds_dwordx4 v[172:173], off
	s_add_i32 m0, s78, 0x2000
	s_add_u32 vcc_lo, s22, 0x80000
	v_lshl_add_u64 v[190:191], s[22:23], 0, v[128:129]
	s_addc_u32 vcc_hi, s23, 0
	s_add_i32 s4, s4, s28
	global_load_lds_dwordx4 v[190:191], off
	v_lshl_add_u64 v[244:245], s[40:41], 0, v[130:131]
	v_lshl_add_u64 v[242:243], s[40:41], 0, v[134:135]
	s_mov_b32 m0, s30
	s_nop 0
	global_load_lds_dwordx4 v[242:243], off
	s_mov_b32 m0, s34
	s_nop 0
	global_load_lds_dwordx4 v[244:245], off
	s_waitcnt vmcnt(6)
	s_waitcnt lgkmcnt(0)
	s_barrier
; #define PG8_STAGE(bufoff, gbase, voff) do { _Pragma("unroll") for (int _i = 0; _i < 2; ++_i) \
;         __builtin_amdgcn_global_load_lds((const unsigned*)((const char*)(gbase) + (voff)[_i]), (LAS unsigned*)(lds + (bufoff) + ldsw + _i * 8192), 16, 0, PG8_AUX); } while (0)
; #define PG8_LDA(dst, b, h) do { _Pragma("unroll") for (int m = 0; m < 4; ++m) _Pragma("unroll") for (int k = 0; k < 2; ++k) dst[m][k] = *(const LAS bf16x8*)(lds + PG8_SA(b, h) + aoff + m * 2048 + k * 1024); } while (0)
; #define PG8_LDB(dst, b, h) do { _Pragma("unroll") for (int n = 0; n < 2; ++n) _Pragma("unroll") for (int k = 0; k < 2; ++k) dst[n][k] = *(const LAS bf16x8*)(lds + PG8_SB(b, h) + boff + n * 2048 + k * 1024); } while (0)
; #define PG8_MMA(ai, bj, At, Bt) do { __builtin_amdgcn_s_setprio(1); _Pragma("unroll") for (int m = 0; m < 4; ++m) _Pragma("unroll") for (int n = 0; n < 2; ++n) _Pragma("unroll") for (int k = 0; k < 2; ++k) \
;         acc[ai][bj][m][n] = __builtin_amdgcn_mfma_f32_16x16x32_bf16(Bt[n][k], At[m][k], acc[ai][bj][m][n], 0, 0, 0); __builtin_amdgcn_s_setprio(0); } while (0)
; #define PG8_WAIT_V(n) asm volatile("s_waitcnt vmcnt(" #n ")" ::: "memory")
; #define PG8_WAIT_L(n) asm volatile("s_waitcnt lgkmcnt(" #n ")" ::: "memory")
; #define PG8_BAR __builtin_amdgcn_s_barrier()
; #define PG8_SCHED __builtin_amdgcn_sched_barrier(0)
; template <class Epi, class Sched>
; __device__ __forceinline__ void gemm_phase(LAS unsigned char* lds, const Gemm g, const Sched& S, const Epi& E) {
;     ...
;             PG8_WAIT_V(8); PG8_WAIT_L(0); PG8_BAR; PG8_MMA(1, 0, At, B0); PG8_MMA(1, 1, At, B1); PG8_BAR; PG8_SCHED;
;             PG8_LDB(B0, 1, 0); PG8_LDB(B1, 1, 1); PG8_SCHED; PG8_LDA(At, 1, 0); PG8_STAGE(PG8_SA(0, 1), a2 + hstepA, voffA);
;             PG8_WAIT_V(8); PG8_WAIT_L(0); PG8_BAR; PG8_MMA(0, 0, At, B0); PG8_MMA(0, 1, At, B1); PG8_BAR; PG8_SCHED;
	s_setprio 1
	s_waitcnt lgkmcnt(0)
	v_mfma_f32_16x16x32_bf16 v[60:63], v[160:163], v[210:213], v[60:63]
	v_mfma_f32_16x16x32_bf16 v[56:59], v[168:171], v[210:213], v[56:59]
	v_mfma_f32_16x16x32_bf16 v[44:47], v[160:163], v[218:221], v[44:47]
	v_mfma_f32_16x16x32_bf16 v[40:43], v[168:171], v[218:221], v[40:43]
	v_mfma_f32_16x16x32_bf16 v[28:31], v[160:163], v[226:229], v[28:31]
	v_mfma_f32_16x16x32_bf16 v[24:27], v[168:171], v[226:229], v[24:27]
	v_mfma_f32_16x16x32_bf16 v[12:15], v[160:163], v[234:237], v[12:15]
	v_mfma_f32_16x16x32_bf16 v[8:11], v[168:171], v[234:237], v[8:11]
	s_setprio 0
	s_setprio 1
	v_mfma_f32_16x16x32_bf16 v[60:63], v[164:167], v[214:217], v[60:63]
	v_mfma_f32_16x16x32_bf16 v[56:59], v[186:189], v[214:217], v[56:59]
	v_mfma_f32_16x16x32_bf16 v[44:47], v[164:167], v[222:225], v[44:47]
	v_mfma_f32_16x16x32_bf16 v[40:43], v[186:189], v[222:225], v[40:43]
	v_mfma_f32_16x16x32_bf16 v[28:31], v[164:167], v[230:233], v[28:31]
	v_mfma_f32_16x16x32_bf16 v[24:27], v[186:189], v[230:233], v[24:27]
	v_mfma_f32_16x16x32_bf16 v[12:15], v[164:167], v[238:241], v[12:15]
	v_mfma_f32_16x16x32_bf16 v[8:11], v[186:189], v[238:241], v[8:11]
	s_setprio 0
	s_setprio 1
	v_mfma_f32_16x16x32_bf16 v[52:55], v[194:197], v[210:213], v[52:55]
	v_mfma_f32_16x16x32_bf16 v[48:51], v[202:205], v[210:213], v[48:51]
	v_mfma_f32_16x16x32_bf16 v[36:39], v[194:197], v[218:221], v[36:39]
	v_mfma_f32_16x16x32_bf16 v[32:35], v[202:205], v[218:221], v[32:35]
	v_mfma_f32_16x16x32_bf16 v[20:23], v[194:197], v[226:229], v[20:23]
	v_mfma_f32_16x16x32_bf16 v[16:19], v[202:205], v[226:229], v[16:19]
	v_mfma_f32_16x16x32_bf16 v[4:7], v[194:197], v[234:237], v[4:7]
	v_mfma_f32_16x16x32_bf16 v[0:3], v[202:205], v[234:237], v[0:3]
	s_setprio 0
	s_setprio 1
	v_mfma_f32_16x16x32_bf16 v[52:55], v[198:201], v[214:217], v[52:55]
	v_mfma_f32_16x16x32_bf16 v[48:51], v[206:209], v[214:217], v[48:51]
	v_mfma_f32_16x16x32_bf16 v[36:39], v[198:201], v[222:225], v[36:39]
	v_mfma_f32_16x16x32_bf16 v[32:35], v[206:209], v[222:225], v[32:35]
	v_mfma_f32_16x16x32_bf16 v[20:23], v[198:201], v[230:233], v[20:23]
	v_mfma_f32_16x16x32_bf16 v[16:19], v[206:209], v[230:233], v[16:19]
	v_mfma_f32_16x16x32_bf16 v[4:7], v[198:201], v[238:241], v[4:7]
	v_mfma_f32_16x16x32_bf16 v[0:3], v[206:209], v[238:241], v[0:3]
	s_setprio 0
	s_barrier
	s_add_i32 s4, 0, 0x18000
	v_add_u32_e32 v136, s4, v182
	s_add_i32 s78, 0, 0x1c000
	ds_read_b128 v[160:163], v136
	ds_read_b128 v[164:167], v136 offset:1024
	ds_read_b128 v[168:171], v136 offset:2048
	ds_read_b128 v[186:189], v136 offset:3072
	v_add_u32_e32 v136, s78, v182
	ds_read_b128 v[194:197], v136
	ds_read_b128 v[198:201], v136 offset:1024
	ds_read_b128 v[202:205], v136 offset:2048
	ds_read_b128 v[206:209], v136 offset:3072
	s_add_u32 s40, s40, 0x80000
	s_addc_u32 s41, s41, 0
	s_mov_b32 m0, s36
	v_lshl_add_u64 v[246:247], s[40:41], 0, v[134:135]
	ds_read_b128 v[210:213], v184 offset:32768
	ds_read_b128 v[214:217], v184 offset:33792
	ds_read_b128 v[218:221], v184 offset:34816
	ds_read_b128 v[222:225], v184 offset:35840
	ds_read_b128 v[226:229], v184 offset:36864
	ds_read_b128 v[230:233], v184 offset:37888
	ds_read_b128 v[234:237], v184 offset:38912
	ds_read_b128 v[238:241], v184 offset:39936
	s_add_u32 s100, s22, 0x80000
	s_addc_u32 s101, s23, 0
	s_add_i32 m0, s28, 0x14000
	s_nop 0
	global_load_lds_dwordx4 v132, s[100:101]
	s_add_i32 m0, s28, 0x16000
	s_nop 0
	global_load_lds_dwordx4 v128, s[100:101]
	s_mov_b32 m0, s36
	s_nop 0
	global_load_lds_dwordx4 v[246:247], off
	v_lshl_add_u64 v[246:247], s[40:41], 0, v[130:131]
	s_mov_b32 m0, s60
	s_nop 0
	global_load_lds_dwordx4 v[246:247], off
	s_waitcnt vmcnt(8)
	s_waitcnt lgkmcnt(0)
	s_barrier
	s_setprio 1
	s_waitcnt lgkmcnt(0)
	v_mfma_f32_16x16x32_bf16 v[124:127], v[160:163], v[210:213], v[124:127]
	v_mfma_f32_16x16x32_bf16 v[120:123], v[168:171], v[210:213], v[120:123]
	v_mfma_f32_16x16x32_bf16 v[108:111], v[160:163], v[218:221], v[108:111]
	v_mfma_f32_16x16x32_bf16 v[104:107], v[168:171], v[218:221], v[104:107]
	v_mfma_f32_16x16x32_bf16 v[92:95], v[160:163], v[226:229], v[92:95]
	v_mfma_f32_16x16x32_bf16 v[88:91], v[168:171], v[226:229], v[88:91]
	v_mfma_f32_16x16x32_bf16 v[76:79], v[160:163], v[234:237], v[76:79]
	v_mfma_f32_16x16x32_bf16 v[72:75], v[168:171], v[234:237], v[72:75]
	s_setprio 0
	s_setprio 1
	v_mfma_f32_16x16x32_bf16 v[124:127], v[164:167], v[214:217], v[124:127]
	v_mfma_f32_16x16x32_bf16 v[120:123], v[186:189], v[214:217], v[120:123]
	v_mfma_f32_16x16x32_bf16 v[108:111], v[164:167], v[222:225], v[108:111]
	v_mfma_f32_16x16x32_bf16 v[104:107], v[186:189], v[222:225], v[104:107]
	v_mfma_f32_16x16x32_bf16 v[92:95], v[164:167], v[230:233], v[92:95]
	v_mfma_f32_16x16x32_bf16 v[88:91], v[186:189], v[230:233], v[88:91]
	v_mfma_f32_16x16x32_bf16 v[76:79], v[164:167], v[238:241], v[76:79]
	v_mfma_f32_16x16x32_bf16 v[72:75], v[186:189], v[238:241], v[72:75]
	s_setprio 0
	s_setprio 1
	v_mfma_f32_16x16x32_bf16 v[116:119], v[194:197], v[210:213], v[116:119]
	v_mfma_f32_16x16x32_bf16 v[112:115], v[202:205], v[210:213], v[112:115]
	v_mfma_f32_16x16x32_bf16 v[100:103], v[194:197], v[218:221], v[100:103]
	v_mfma_f32_16x16x32_bf16 v[96:99], v[202:205], v[218:221], v[96:99]
	v_mfma_f32_16x16x32_bf16 v[84:87], v[194:197], v[226:229], v[84:87]
	v_mfma_f32_16x16x32_bf16 v[80:83], v[202:205], v[226:229], v[80:83]
	v_mfma_f32_16x16x32_bf16 v[68:71], v[194:197], v[234:237], v[68:71]
	v_mfma_f32_16x16x32_bf16 v[64:67], v[202:205], v[234:237], v[64:67]
	s_setprio 0
	s_setprio 1
	v_mfma_f32_16x16x32_bf16 v[116:119], v[198:201], v[214:217], v[116:119]
	v_mfma_f32_16x16x32_bf16 v[112:115], v[206:209], v[214:217], v[112:115]
	v_mfma_f32_16x16x32_bf16 v[100:103], v[198:201], v[222:225], v[100:103]
	v_mfma_f32_16x16x32_bf16 v[96:99], v[206:209], v[222:225], v[96:99]
	v_mfma_f32_16x16x32_bf16 v[84:87], v[198:201], v[230:233], v[84:87]
	v_mfma_f32_16x16x32_bf16 v[80:83], v[206:209], v[230:233], v[80:83]
	v_mfma_f32_16x16x32_bf16 v[68:71], v[198:201], v[238:241], v[68:71]
	v_mfma_f32_16x16x32_bf16 v[64:67], v[206:209], v[238:241], v[64:67]
	s_setprio 0
	s_barrier
; #define PG8_STAGE(bufoff, gbase, voff) do { _Pragma("unroll") for (int _i = 0; _i < 2; ++_i) \
;         __builtin_amdgcn_global_load_lds((const unsigned*)((const char*)(gbase) + (voff)[_i]), (LAS unsigned*)(lds + (bufoff) + ldsw + _i * 8192), 16, 0, PG8_AUX); } while (0)
; #define PG8_LDA(dst, b, h) do { _Pragma("unroll") for (int m = 0; m < 4; ++m) _Pragma("unroll") for (int k = 0; k < 2; ++k) dst[m][k] = *(const LAS bf16x8*)(lds + PG8_SA(b, h) + aoff + m * 2048 + k * 1024); } while (0)
; #define PG8_MMA(ai, bj, At, Bt) do { __builtin_amdgcn_s_setprio(1); _Pragma("unroll") for (int m = 0; m < 4; ++m) _Pragma("unroll") for (int n = 0; n < 2; ++n) _Pragma("unroll") for (int k = 0; k < 2; ++k) \
;         acc[ai][bj][m][n] = __builtin_amdgcn_mfma_f32_16x16x32_bf16(Bt[n][k], At[m][k], acc[ai][bj][m][n], 0, 0, 0); __builtin_amdgcn_s_setprio(0); } while (0)
; #define PG8_WAIT_V(n) asm volatile("s_waitcnt vmcnt(" #n ")" ::: "memory")
; #define PG8_WAIT_L(n) asm volatile("s_waitcnt lgkmcnt(" #n ")" ::: "memory")
; #define PG8_BAR __builtin_amdgcn_s_barrier()
; #define PG8_SCHED __builtin_amdgcn_sched_barrier(0)
; template <class Epi, class Sched>
; __device__ __forceinline__ void gemm_phase(LAS unsigned char* lds, const Gemm g, const Sched& S, const Epi& E) {
;     ...
;             PG8_LDA(At, 1, 1); PG8_STAGE(PG8_SB(1, 0), b3, voffB); PG8_STAGE(PG8_SB(1, 1), b3 + hstepB, voffB); PG8_STAGE(PG8_SA(1, 0), a3, voffA);
;             PG8_WAIT_V(8); PG8_WAIT_L(0); PG8_BAR; PG8_MMA(1, 0, At, B0); PG8_MMA(1, 1, At, B1); PG8_BAR; PG8_SCHED;
	s_add_i32 s4, s4, s28
	v_lshl_add_u64 v[172:173], v[172:173], 0, s[12:13]
	s_mov_b32 m0, s4
	ds_read_b128 v[210:213], v184 offset:49152
	ds_read_b128 v[214:217], v184 offset:50176
	ds_read_b128 v[218:221], v184 offset:51200
	ds_read_b128 v[222:225], v184 offset:52224
	ds_read_b128 v[226:229], v184 offset:53248
	ds_read_b128 v[230:233], v184 offset:54272
	ds_read_b128 v[234:237], v184 offset:55296
	ds_read_b128 v[238:241], v184 offset:56320
	global_load_lds_dwordx4 v[172:173], off
	s_add_i32 m0, s4, 0x2000
	s_add_u32 s22, s22, 0x80080
	v_lshl_add_u64 v[172:173], v[190:191], 0, s[12:13]
	s_addc_u32 s23, s23, 0
	s_add_i32 s4, s78, s28
	global_load_lds_dwordx4 v[172:173], off
	v_lshl_add_u64 v[172:173], s[22:23], 0, v[132:133]
	s_mov_b32 m0, s4
	s_nop 0
	global_load_lds_dwordx4 v[172:173], off
	v_lshl_add_u64 v[172:173], s[22:23], 0, v[128:129]
	s_add_i32 m0, s4, 0x2000
	s_nop 0
	global_load_lds_dwordx4 v[172:173], off
	v_lshl_add_u64 v[172:173], v[242:243], 0, s[12:13]
	s_mov_b32 m0, s61
	s_nop 0
	global_load_lds_dwordx4 v[172:173], off
	v_lshl_add_u64 v[172:173], v[244:245], 0, s[12:13]
	s_mov_b32 m0, s62
	s_nop 0
	global_load_lds_dwordx4 v[172:173], off
	s_waitcnt vmcnt(8)
	s_waitcnt lgkmcnt(0)
	s_barrier
	s_setprio 1
	s_waitcnt lgkmcnt(0)
	v_mfma_f32_16x16x32_bf16 v[60:63], v[160:163], v[210:213], v[60:63]
	v_mfma_f32_16x16x32_bf16 v[56:59], v[168:171], v[210:213], v[56:59]
	v_mfma_f32_16x16x32_bf16 v[44:47], v[160:163], v[218:221], v[44:47]
	v_mfma_f32_16x16x32_bf16 v[40:43], v[168:171], v[218:221], v[40:43]
	v_mfma_f32_16x16x32_bf16 v[28:31], v[160:163], v[226:229], v[28:31]
	v_mfma_f32_16x16x32_bf16 v[24:27], v[168:171], v[226:229], v[24:27]
	v_mfma_f32_16x16x32_bf16 v[12:15], v[160:163], v[234:237], v[12:15]
	v_mfma_f32_16x16x32_bf16 v[8:11], v[168:171], v[234:237], v[8:11]
	s_setprio 0
	s_setprio 1
	v_mfma_f32_16x16x32_bf16 v[60:63], v[164:167], v[214:217], v[60:63]
	v_mfma_f32_16x16x32_bf16 v[56:59], v[186:189], v[214:217], v[56:59]
	v_mfma_f32_16x16x32_bf16 v[44:47], v[164:167], v[222:225], v[44:47]
	v_mfma_f32_16x16x32_bf16 v[40:43], v[186:189], v[222:225], v[40:43]
	v_mfma_f32_16x16x32_bf16 v[28:31], v[164:167], v[230:233], v[28:31]
	v_mfma_f32_16x16x32_bf16 v[24:27], v[186:189], v[230:233], v[24:27]
	v_mfma_f32_16x16x32_bf16 v[12:15], v[164:167], v[238:241], v[12:15]
	v_mfma_f32_16x16x32_bf16 v[8:11], v[186:189], v[238:241], v[8:11]
	s_setprio 0
	s_setprio 1
	v_mfma_f32_16x16x32_bf16 v[52:55], v[194:197], v[210:213], v[52:55]
	v_mfma_f32_16x16x32_bf16 v[48:51], v[202:205], v[210:213], v[48:51]
	v_mfma_f32_16x16x32_bf16 v[36:39], v[194:197], v[218:221], v[36:39]
	v_mfma_f32_16x16x32_bf16 v[32:35], v[202:205], v[218:221], v[32:35]
	v_mfma_f32_16x16x32_bf16 v[20:23], v[194:197], v[226:229], v[20:23]
	v_mfma_f32_16x16x32_bf16 v[16:19], v[202:205], v[226:229], v[16:19]
	v_mfma_f32_16x16x32_bf16 v[4:7], v[194:197], v[234:237], v[4:7]
	v_mfma_f32_16x16x32_bf16 v[0:3], v[202:205], v[234:237], v[0:3]
	s_setprio 0
	s_setprio 1
	v_mfma_f32_16x16x32_bf16 v[52:55], v[198:201], v[214:217], v[52:55]
	v_mfma_f32_16x16x32_bf16 v[48:51], v[206:209], v[214:217], v[48:51]
	v_mfma_f32_16x16x32_bf16 v[36:39], v[198:201], v[222:225], v[36:39]
	v_mfma_f32_16x16x32_bf16 v[32:35], v[206:209], v[222:225], v[32:35]
	v_mfma_f32_16x16x32_bf16 v[20:23], v[198:201], v[230:233], v[20:23]
	v_mfma_f32_16x16x32_bf16 v[16:19], v[206:209], v[230:233], v[16:19]
	v_mfma_f32_16x16x32_bf16 v[4:7], v[198:201], v[238:241], v[4:7]
	v_mfma_f32_16x16x32_bf16 v[0:3], v[206:209], v[238:241], v[0:3]
	s_setprio 0
	s_barrier
	s_add_i32 s65, s65, 2
	s_add_u32 s0, s0, 0x100
	s_addc_u32 s1, s1, 0
	s_add_u32 s63, s63, 0x100
	s_addc_u32 s64, s64, 0
	s_cmp_gt_u32 s65, 29
	s_cbranch_scc0 .LBB0_382
	s_and_b64 vcc, exec, s[46:47]
	s_cbranch_vccz .LBB0_385
	s_barrier

; #define PG8_STAGE(bufoff, gbase, voff) do { _Pragma("unroll") for (int _i = 0; _i < 2; ++_i) \
;         __builtin_amdgcn_global_load_lds((const unsigned*)((const char*)(gbase) + (voff)[_i]), (LAS unsigned*)(lds + (bufoff) + ldsw + _i * 8192), 16, 0, PG8_AUX); } while (0)
; #define PG8_LDA(dst, b, h) do { _Pragma("unroll") for (int m = 0; m < 4; ++m) _Pragma("unroll") for (int k = 0; k < 2; ++k) dst[m][k] = *(const LAS bf16x8*)(lds + PG8_SA(b, h) + aoff + m * 2048 + k * 1024); } while (0)
; #define PG8_LDB(dst, b, h) do { _Pragma("unroll") for (int n = 0; n < 2; ++n) _Pragma("unroll") for (int k = 0; k < 2; ++k) dst[n][k] = *(const LAS bf16x8*)(lds + PG8_SB(b, h) + boff + n * 2048 + k * 1024); } while (0)
; #define PG8_MMA(ai, bj, At, Bt) do { __builtin_amdgcn_s_setprio(1); _Pragma("unroll") for (int m = 0; m < 4; ++m) _Pragma("unroll") for (int n = 0; n < 2; ++n) _Pragma("unroll") for (int k = 0; k < 2; ++k) \
;         acc[ai][bj][m][n] = __builtin_amdgcn_mfma_f32_16x16x32_bf16(Bt[n][k], At[m][k], acc[ai][bj][m][n], 0, 0, 0); __builtin_amdgcn_s_setprio(0); } while (0)
; #define PG8_WAIT_V(n) asm volatile("s_waitcnt vmcnt(" #n ")" ::: "memory")
; #define PG8_WAIT_L(n) asm volatile("s_waitcnt lgkmcnt(" #n ")" ::: "memory")
; #define PG8_BAR __builtin_amdgcn_s_barrier()
; #define PG8_SCHED __builtin_amdgcn_sched_barrier(0)
; template <class Epi, class Sched>
; __device__ __forceinline__ void gemm_phase(LAS unsigned char* lds, const Gemm g, const Sched& S, const Epi& E) {
;     ...
;         for (int t = 0; t < nt; t += 2) {
;             const bool last = (t == nt - 2);
;             const char* a1 = cA + (size_t)(t + 1) * kstep;
;             const char* a2 = last ? nA : cA + (size_t)(t + 2) * kstep; const char* b2 = last ? nB : cB + (size_t)(t + 2) * kstep;
;             const char* a3 = a2 + kstep; const char* b3 = b2 + kstep;
;     ...
;             PG8_LDB(B0, 0, 0); PG8_LDB(B1, 0, 1); PG8_SCHED; PG8_LDA(At, 0, 0); PG8_STAGE(PG8_SA(1, 1), a1 + hstepA, voffA);
;             PG8_WAIT_V(8); PG8_WAIT_L(0); PG8_BAR; PG8_MMA(0, 0, At, B0); PG8_MMA(0, 1, At, B1); PG8_BAR; PG8_SCHED;
;             PG8_LDA(At, 0, 1); PG8_STAGE(PG8_SB(0, 0), b2, voffB); PG8_STAGE(PG8_SB(0, 1), b2 + hstepB, voffB); PG8_STAGE(PG8_SA(0, 0), a2, voffA);
;             PG8_WAIT_V(8); PG8_WAIT_L(0); PG8_BAR; PG8_MMA(1, 0, At, B0); PG8_MMA(1, 1, At, B1); PG8_BAR; PG8_SCHED;
.LBB0_679:
	s_add_u32 s54, s42, 0x100
	s_addc_u32 s55, s43, 0
	s_add_i32 s78, 0, 0x10000
	s_cmpk_eq_i32 s4, 0x54
	s_cselect_b32 s63, s1, s55
	s_cselect_b32 s62, s0, s54
	v_add_u32_e32 v164, s78, v167
	s_cselect_b32 s57, s53, vcc_hi
	s_cselect_b32 s56, s52, vcc_lo
	s_add_i32 s79, 0, 0x14000
	ds_read_b128 v[156:159], v164
	ds_read_b128 v[160:163], v164 offset:1024
	ds_read_b128 v[170:173], v164 offset:2048
	ds_read_b128 v[182:185], v164 offset:3072
	v_add_u32_e32 v164, s79, v167
	ds_read_b128 v[186:189], v164
	ds_read_b128 v[194:197], v164 offset:1024
	ds_read_b128 v[198:201], v164 offset:2048
	ds_read_b128 v[202:205], v164 offset:3072
	v_lshl_add_u64 v[164:165], s[42:43], 0, v[134:135]
	s_add_i32 m0, s36, 0xc000
	ds_read_b128 v[206:209], v169
	ds_read_b128 v[210:213], v169 offset:1024
	ds_read_b128 v[214:217], v169 offset:2048
	ds_read_b128 v[218:221], v169 offset:3072
	ds_read_b128 v[222:225], v169 offset:4096
	ds_read_b128 v[226:229], v169 offset:5120
	ds_read_b128 v[230:233], v169 offset:6144
	ds_read_b128 v[234:237], v169 offset:7168
	global_load_lds_dwordx4 v[164:165], off
	v_lshl_add_u64 v[164:165], s[42:43], 0, v[154:155]
	s_add_i32 m0, s36, 0xe000
	s_nop 0
	global_load_lds_dwordx4 v[164:165], off
	s_waitcnt vmcnt(8)
	s_waitcnt lgkmcnt(0)
	s_barrier
	s_setprio 1
	s_waitcnt lgkmcnt(0)
	v_mfma_f32_16x16x32_bf16 v[124:127], v[156:159], v[206:209], v[124:127]
	v_mfma_f32_16x16x32_bf16 v[120:123], v[170:173], v[206:209], v[120:123]
	v_mfma_f32_16x16x32_bf16 v[108:111], v[156:159], v[214:217], v[108:111]
	v_mfma_f32_16x16x32_bf16 v[104:107], v[170:173], v[214:217], v[104:107]
	v_mfma_f32_16x16x32_bf16 v[92:95], v[156:159], v[222:225], v[92:95]
	v_mfma_f32_16x16x32_bf16 v[88:91], v[170:173], v[222:225], v[88:91]
	v_mfma_f32_16x16x32_bf16 v[76:79], v[156:159], v[230:233], v[76:79]
	v_mfma_f32_16x16x32_bf16 v[72:75], v[170:173], v[230:233], v[72:75]
	s_setprio 0
	s_setprio 1
	v_mfma_f32_16x16x32_bf16 v[124:127], v[160:163], v[210:213], v[124:127]
	v_mfma_f32_16x16x32_bf16 v[120:123], v[182:185], v[210:213], v[120:123]
	v_mfma_f32_16x16x32_bf16 v[108:111], v[160:163], v[218:221], v[108:111]
	v_mfma_f32_16x16x32_bf16 v[104:107], v[182:185], v[218:221], v[104:107]
	v_mfma_f32_16x16x32_bf16 v[92:95], v[160:163], v[226:229], v[92:95]
	v_mfma_f32_16x16x32_bf16 v[88:91], v[182:185], v[226:229], v[88:91]
	v_mfma_f32_16x16x32_bf16 v[76:79], v[160:163], v[234:237], v[76:79]
	v_mfma_f32_16x16x32_bf16 v[72:75], v[182:185], v[234:237], v[72:75]
	s_setprio 0
	s_setprio 1
	v_mfma_f32_16x16x32_bf16 v[116:119], v[186:189], v[206:209], v[116:119]
	v_mfma_f32_16x16x32_bf16 v[112:115], v[198:201], v[206:209], v[112:115]
	v_mfma_f32_16x16x32_bf16 v[100:103], v[186:189], v[214:217], v[100:103]
	v_mfma_f32_16x16x32_bf16 v[96:99], v[198:201], v[214:217], v[96:99]
	v_mfma_f32_16x16x32_bf16 v[84:87], v[186:189], v[222:225], v[84:87]
	v_mfma_f32_16x16x32_bf16 v[80:83], v[198:201], v[222:225], v[80:83]
	v_mfma_f32_16x16x32_bf16 v[68:71], v[186:189], v[230:233], v[68:71]
	v_mfma_f32_16x16x32_bf16 v[64:67], v[198:201], v[230:233], v[64:67]
	s_setprio 0
	s_setprio 1
	v_mfma_f32_16x16x32_bf16 v[116:119], v[194:197], v[210:213], v[116:119]
	v_mfma_f32_16x16x32_bf16 v[112:115], v[202:205], v[210:213], v[112:115]
	v_mfma_f32_16x16x32_bf16 v[100:103], v[194:197], v[218:221], v[100:103]
	v_mfma_f32_16x16x32_bf16 v[96:99], v[202:205], v[218:221], v[96:99]
	v_mfma_f32_16x16x32_bf16 v[84:87], v[194:197], v[226:229], v[84:87]
	v_mfma_f32_16x16x32_bf16 v[80:83], v[202:205], v[226:229], v[80:83]
	v_mfma_f32_16x16x32_bf16 v[68:71], v[194:197], v[234:237], v[68:71]
	v_mfma_f32_16x16x32_bf16 v[64:67], v[202:205], v[234:237], v[64:67]
	s_setprio 0
	s_barrier
	s_add_i32 s42, s78, s34
	v_lshl_add_u64 v[164:165], s[56:57], 0, v[136:137]
	s_mov_b32 m0, s42
	ds_read_b128 v[206:209], v169 offset:16384
	ds_read_b128 v[210:213], v169 offset:17408
	ds_read_b128 v[214:217], v169 offset:18432
	ds_read_b128 v[218:221], v169 offset:19456
	ds_read_b128 v[222:225], v169 offset:20480
	ds_read_b128 v[226:229], v169 offset:21504
	ds_read_b128 v[230:233], v169 offset:22528
	ds_read_b128 v[234:237], v169 offset:23552
	global_load_lds_dwordx4 v[164:165], off
	s_add_i32 m0, s42, 0x2000
	s_add_u32 s42, s56, 0x160000
	v_lshl_add_u64 v[190:191], s[56:57], 0, v[128:129]
	s_addc_u32 s43, s57, 0
	s_add_i32 s78, s79, s34
	global_load_lds_dwordx4 v[190:191], off
	v_lshl_add_u64 v[238:239], s[42:43], 0, v[136:137]
	s_mov_b32 m0, s78
	v_lshl_add_u64 v[240:241], s[62:63], 0, v[130:131]
	global_load_lds_dwordx4 v[238:239], off
	v_lshl_add_u64 v[238:239], s[42:43], 0, v[128:129]
	s_add_i32 m0, s78, 0x2000
	s_nop 0
	global_load_lds_dwordx4 v[238:239], off
	v_lshl_add_u64 v[238:239], s[62:63], 0, v[132:133]
	s_mov_b32 m0, s36
	s_nop 0
	global_load_lds_dwordx4 v[238:239], off
	s_mov_b32 m0, s64
	s_nop 0
	global_load_lds_dwordx4 v[240:241], off
	s_waitcnt vmcnt(8)
	s_waitcnt lgkmcnt(0)
	s_barrier
; #define PG8_STAGE(bufoff, gbase, voff) do { _Pragma("unroll") for (int _i = 0; _i < 2; ++_i) \
;         __builtin_amdgcn_global_load_lds((const unsigned*)((const char*)(gbase) + (voff)[_i]), (LAS unsigned*)(lds + (bufoff) + ldsw + _i * 8192), 16, 0, PG8_AUX); } while (0)
; #define PG8_LDA(dst, b, h) do { _Pragma("unroll") for (int m = 0; m < 4; ++m) _Pragma("unroll") for (int k = 0; k < 2; ++k) dst[m][k] = *(const LAS bf16x8*)(lds + PG8_SA(b, h) + aoff + m * 2048 + k * 1024); } while (0)
; #define PG8_LDB(dst, b, h) do { _Pragma("unroll") for (int n = 0; n < 2; ++n) _Pragma("unroll") for (int k = 0; k < 2; ++k) dst[n][k] = *(const LAS bf16x8*)(lds + PG8_SB(b, h) + boff + n * 2048 + k * 1024); } while (0)
; #define PG8_MMA(ai, bj, At, Bt) do { __builtin_amdgcn_s_setprio(1); _Pragma("unroll") for (int m = 0; m < 4; ++m) _Pragma("unroll") for (int n = 0; n < 2; ++n) _Pragma("unroll") for (int k = 0; k < 2; ++k) \
;         acc[ai][bj][m][n] = __builtin_amdgcn_mfma_f32_16x16x32_bf16(Bt[n][k], At[m][k], acc[ai][bj][m][n], 0, 0, 0); __builtin_amdgcn_s_setprio(0); } while (0)
; #define PG8_WAIT_V(n) asm volatile("s_waitcnt vmcnt(" #n ")" ::: "memory")
; #define PG8_WAIT_L(n) asm volatile("s_waitcnt lgkmcnt(" #n ")" ::: "memory")
; #define PG8_BAR __builtin_amdgcn_s_barrier()
; #define PG8_SCHED __builtin_amdgcn_sched_barrier(0)
; template <class Epi, class Sched>
; __device__ __forceinline__ void gemm_phase(LAS unsigned char* lds, const Gemm g, const Sched& S, const Epi& E) {
;     ...
;             PG8_WAIT_V(8); PG8_WAIT_L(0); PG8_BAR; PG8_MMA(1, 0, At, B0); PG8_MMA(1, 1, At, B1); PG8_BAR; PG8_SCHED;
;             PG8_LDB(B0, 1, 0); PG8_LDB(B1, 1, 1); PG8_SCHED; PG8_LDA(At, 1, 0); PG8_STAGE(PG8_SA(0, 1), a2 + hstepA, voffA);
;             PG8_WAIT_V(8); PG8_WAIT_L(0); PG8_BAR; PG8_MMA(0, 0, At, B0); PG8_MMA(0, 1, At, B1); PG8_BAR; PG8_SCHED;
	s_setprio 1
	s_waitcnt lgkmcnt(0)
	v_mfma_f32_16x16x32_bf16 v[60:63], v[156:159], v[206:209], v[60:63]
	v_mfma_f32_16x16x32_bf16 v[56:59], v[170:173], v[206:209], v[56:59]
	v_mfma_f32_16x16x32_bf16 v[44:47], v[156:159], v[214:217], v[44:47]
	v_mfma_f32_16x16x32_bf16 v[40:43], v[170:173], v[214:217], v[40:43]
	v_mfma_f32_16x16x32_bf16 v[28:31], v[156:159], v[222:225], v[28:31]
	v_mfma_f32_16x16x32_bf16 v[24:27], v[170:173], v[222:225], v[24:27]
	v_mfma_f32_16x16x32_bf16 v[12:15], v[156:159], v[230:233], v[12:15]
	v_mfma_f32_16x16x32_bf16 v[8:11], v[170:173], v[230:233], v[8:11]
	s_setprio 0
	s_setprio 1
	v_mfma_f32_16x16x32_bf16 v[60:63], v[160:163], v[210:213], v[60:63]
	v_mfma_f32_16x16x32_bf16 v[56:59], v[182:185], v[210:213], v[56:59]
	v_mfma_f32_16x16x32_bf16 v[44:47], v[160:163], v[218:221], v[44:47]
	v_mfma_f32_16x16x32_bf16 v[40:43], v[182:185], v[218:221], v[40:43]
	v_mfma_f32_16x16x32_bf16 v[28:31], v[160:163], v[226:229], v[28:31]
	v_mfma_f32_16x16x32_bf16 v[24:27], v[182:185], v[226:229], v[24:27]
	v_mfma_f32_16x16x32_bf16 v[12:15], v[160:163], v[234:237], v[12:15]
	v_mfma_f32_16x16x32_bf16 v[8:11], v[182:185], v[234:237], v[8:11]
	s_setprio 0
	s_setprio 1
	v_mfma_f32_16x16x32_bf16 v[52:55], v[186:189], v[206:209], v[52:55]
	v_mfma_f32_16x16x32_bf16 v[48:51], v[198:201], v[206:209], v[48:51]
	v_mfma_f32_16x16x32_bf16 v[36:39], v[186:189], v[214:217], v[36:39]
	v_mfma_f32_16x16x32_bf16 v[32:35], v[198:201], v[214:217], v[32:35]
	v_mfma_f32_16x16x32_bf16 v[20:23], v[186:189], v[222:225], v[20:23]
	v_mfma_f32_16x16x32_bf16 v[16:19], v[198:201], v[222:225], v[16:19]
	v_mfma_f32_16x16x32_bf16 v[4:7], v[186:189], v[230:233], v[4:7]
	v_mfma_f32_16x16x32_bf16 v[0:3], v[198:201], v[230:233], v[0:3]
	s_setprio 0
	s_setprio 1
	v_mfma_f32_16x16x32_bf16 v[52:55], v[194:197], v[210:213], v[52:55]
	v_mfma_f32_16x16x32_bf16 v[48:51], v[202:205], v[210:213], v[48:51]
	v_mfma_f32_16x16x32_bf16 v[36:39], v[194:197], v[218:221], v[36:39]
	v_mfma_f32_16x16x32_bf16 v[32:35], v[202:205], v[218:221], v[32:35]
	v_mfma_f32_16x16x32_bf16 v[20:23], v[194:197], v[226:229], v[20:23]
	v_mfma_f32_16x16x32_bf16 v[16:19], v[202:205], v[226:229], v[16:19]
	v_mfma_f32_16x16x32_bf16 v[4:7], v[194:197], v[234:237], v[4:7]
	v_mfma_f32_16x16x32_bf16 v[0:3], v[202:205], v[234:237], v[0:3]
	s_setprio 0
	s_barrier
	s_add_i32 s78, 0, 0x18000
	v_add_u32_e32 v181, s78, v167
	s_add_i32 s79, 0, 0x1c000
	ds_read_b128 v[156:159], v181
	ds_read_b128 v[160:163], v181 offset:1024
	ds_read_b128 v[170:173], v181 offset:2048
	ds_read_b128 v[182:185], v181 offset:3072
	v_add_u32_e32 v181, s79, v167
	ds_read_b128 v[186:189], v181
	ds_read_b128 v[194:197], v181 offset:1024
	ds_read_b128 v[198:201], v181 offset:2048
	ds_read_b128 v[202:205], v181 offset:3072
	s_add_u32 s42, s62, 0x160000
	s_addc_u32 s43, s63, 0
	s_mov_b32 m0, s65
	v_lshl_add_u64 v[242:243], s[42:43], 0, v[132:133]
	ds_read_b128 v[206:209], v169 offset:32768
	ds_read_b128 v[210:213], v169 offset:33792
	ds_read_b128 v[214:217], v169 offset:34816
	ds_read_b128 v[218:221], v169 offset:35840
	ds_read_b128 v[222:225], v169 offset:36864
	ds_read_b128 v[226:229], v169 offset:37888
	ds_read_b128 v[230:233], v169 offset:38912
	ds_read_b128 v[234:237], v169 offset:39936
	global_load_lds_dwordx4 v[242:243], off
	v_lshl_add_u64 v[242:243], s[42:43], 0, v[130:131]
	s_mov_b32 m0, s92
	s_nop 0
	global_load_lds_dwordx4 v[242:243], off
	s_waitcnt vmcnt(8)
	s_waitcnt lgkmcnt(0)
	s_barrier
	s_setprio 1
	s_waitcnt lgkmcnt(0)
	v_mfma_f32_16x16x32_bf16 v[124:127], v[156:159], v[206:209], v[124:127]
	v_mfma_f32_16x16x32_bf16 v[120:123], v[170:173], v[206:209], v[120:123]
	v_mfma_f32_16x16x32_bf16 v[108:111], v[156:159], v[214:217], v[108:111]
	v_mfma_f32_16x16x32_bf16 v[104:107], v[170:173], v[214:217], v[104:107]
	v_mfma_f32_16x16x32_bf16 v[92:95], v[156:159], v[222:225], v[92:95]
	v_mfma_f32_16x16x32_bf16 v[88:91], v[170:173], v[222:225], v[88:91]
	v_mfma_f32_16x16x32_bf16 v[76:79], v[156:159], v[230:233], v[76:79]
	v_mfma_f32_16x16x32_bf16 v[72:75], v[170:173], v[230:233], v[72:75]
	s_setprio 0
	s_setprio 1
	v_mfma_f32_16x16x32_bf16 v[124:127], v[160:163], v[210:213], v[124:127]
	v_mfma_f32_16x16x32_bf16 v[120:123], v[182:185], v[210:213], v[120:123]
	v_mfma_f32_16x16x32_bf16 v[108:111], v[160:163], v[218:221], v[108:111]
	v_mfma_f32_16x16x32_bf16 v[104:107], v[182:185], v[218:221], v[104:107]
	v_mfma_f32_16x16x32_bf16 v[92:95], v[160:163], v[226:229], v[92:95]
	v_mfma_f32_16x16x32_bf16 v[88:91], v[182:185], v[226:229], v[88:91]
	v_mfma_f32_16x16x32_bf16 v[76:79], v[160:163], v[234:237], v[76:79]
	v_mfma_f32_16x16x32_bf16 v[72:75], v[182:185], v[234:237], v[72:75]
	s_setprio 0
	s_setprio 1
	v_mfma_f32_16x16x32_bf16 v[116:119], v[186:189], v[206:209], v[116:119]
	v_mfma_f32_16x16x32_bf16 v[112:115], v[198:201], v[206:209], v[112:115]
	v_mfma_f32_16x16x32_bf16 v[100:103], v[186:189], v[214:217], v[100:103]
	v_mfma_f32_16x16x32_bf16 v[96:99], v[198:201], v[214:217], v[96:99]
	v_mfma_f32_16x16x32_bf16 v[84:87], v[186:189], v[222:225], v[84:87]
	v_mfma_f32_16x16x32_bf16 v[80:83], v[198:201], v[222:225], v[80:83]
	v_mfma_f32_16x16x32_bf16 v[68:71], v[186:189], v[230:233], v[68:71]
	v_mfma_f32_16x16x32_bf16 v[64:67], v[198:201], v[230:233], v[64:67]
	s_setprio 0
	s_setprio 1
	v_mfma_f32_16x16x32_bf16 v[116:119], v[194:197], v[210:213], v[116:119]
	v_mfma_f32_16x16x32_bf16 v[112:115], v[202:205], v[210:213], v[112:115]
	v_mfma_f32_16x16x32_bf16 v[100:103], v[194:197], v[218:221], v[100:103]
	v_mfma_f32_16x16x32_bf16 v[96:99], v[202:205], v[218:221], v[96:99]
	v_mfma_f32_16x16x32_bf16 v[84:87], v[194:197], v[226:229], v[84:87]
	v_mfma_f32_16x16x32_bf16 v[80:83], v[202:205], v[226:229], v[80:83]
	v_mfma_f32_16x16x32_bf16 v[68:71], v[194:197], v[234:237], v[68:71]
	v_mfma_f32_16x16x32_bf16 v[64:67], v[202:205], v[234:237], v[64:67]
	s_setprio 0
	s_barrier
; #define PG8_STAGE(bufoff, gbase, voff) do { _Pragma("unroll") for (int _i = 0; _i < 2; ++_i) \
;         __builtin_amdgcn_global_load_lds((const unsigned*)((const char*)(gbase) + (voff)[_i]), (LAS unsigned*)(lds + (bufoff) + ldsw + _i * 8192), 16, 0, PG8_AUX); } while (0)
; #define PG8_LDA(dst, b, h) do { _Pragma("unroll") for (int m = 0; m < 4; ++m) _Pragma("unroll") for (int k = 0; k < 2; ++k) dst[m][k] = *(const LAS bf16x8*)(lds + PG8_SA(b, h) + aoff + m * 2048 + k * 1024); } while (0)
; #define PG8_MMA(ai, bj, At, Bt) do { __builtin_amdgcn_s_setprio(1); _Pragma("unroll") for (int m = 0; m < 4; ++m) _Pragma("unroll") for (int n = 0; n < 2; ++n) _Pragma("unroll") for (int k = 0; k < 2; ++k) \
;         acc[ai][bj][m][n] = __builtin_amdgcn_mfma_f32_16x16x32_bf16(Bt[n][k], At[m][k], acc[ai][bj][m][n], 0, 0, 0); __builtin_amdgcn_s_setprio(0); } while (0)
; #define PG8_WAIT_V(n) asm volatile("s_waitcnt vmcnt(" #n ")" ::: "memory")
; #define PG8_WAIT_L(n) asm volatile("s_waitcnt lgkmcnt(" #n ")" ::: "memory")
; #define PG8_BAR __builtin_amdgcn_s_barrier()
; #define PG8_SCHED __builtin_amdgcn_sched_barrier(0)
; template <class Epi, class Sched>
; __device__ __forceinline__ void gemm_phase(LAS unsigned char* lds, const Gemm g, const Sched& S, const Epi& E) {
;     ...
;             PG8_LDA(At, 1, 1); PG8_STAGE(PG8_SB(1, 0), b3, voffB); PG8_STAGE(PG8_SB(1, 1), b3 + hstepB, voffB); PG8_STAGE(PG8_SA(1, 0), a3, voffA);
;             PG8_WAIT_V(8); PG8_WAIT_L(0); PG8_BAR; PG8_MMA(1, 0, At, B0); PG8_MMA(1, 1, At, B1); PG8_BAR; PG8_SCHED;
	s_add_i32 s42, s78, s34
	v_lshl_add_u64 v[164:165], v[164:165], 0, s[12:13]
	s_mov_b32 m0, s42
	ds_read_b128 v[206:209], v169 offset:49152
	ds_read_b128 v[210:213], v169 offset:50176
	ds_read_b128 v[214:217], v169 offset:51200
	ds_read_b128 v[218:221], v169 offset:52224
	ds_read_b128 v[222:225], v169 offset:53248
	ds_read_b128 v[226:229], v169 offset:54272
	ds_read_b128 v[230:233], v169 offset:55296
	ds_read_b128 v[234:237], v169 offset:56320
	global_load_lds_dwordx4 v[164:165], off
	s_add_i32 m0, s42, 0x2000
	s_add_u32 s42, s56, 0x160080
	v_lshl_add_u64 v[164:165], v[190:191], 0, s[12:13]
	s_addc_u32 s43, s57, 0
	s_add_i32 s56, s79, s34
	global_load_lds_dwordx4 v[164:165], off
	v_lshl_add_u64 v[164:165], s[42:43], 0, v[136:137]
	s_mov_b32 m0, s56
	s_nop 0
	global_load_lds_dwordx4 v[164:165], off
	v_lshl_add_u64 v[164:165], s[42:43], 0, v[128:129]
	s_add_i32 m0, s56, 0x2000
	s_nop 0
	global_load_lds_dwordx4 v[164:165], off
	v_lshl_add_u64 v[164:165], v[238:239], 0, s[12:13]
	s_mov_b32 m0, s94
	s_nop 0
	global_load_lds_dwordx4 v[164:165], off
	v_lshl_add_u64 v[164:165], v[240:241], 0, s[12:13]
	s_mov_b32 m0, s96
	s_nop 0
	global_load_lds_dwordx4 v[164:165], off
	s_waitcnt vmcnt(8)
	s_waitcnt lgkmcnt(0)
	s_barrier
	s_setprio 1
	s_waitcnt lgkmcnt(0)
	v_mfma_f32_16x16x32_bf16 v[60:63], v[156:159], v[206:209], v[60:63]
	v_mfma_f32_16x16x32_bf16 v[56:59], v[170:173], v[206:209], v[56:59]
	v_mfma_f32_16x16x32_bf16 v[44:47], v[156:159], v[214:217], v[44:47]
	v_mfma_f32_16x16x32_bf16 v[40:43], v[170:173], v[214:217], v[40:43]
	v_mfma_f32_16x16x32_bf16 v[28:31], v[156:159], v[222:225], v[28:31]
	v_mfma_f32_16x16x32_bf16 v[24:27], v[170:173], v[222:225], v[24:27]
	v_mfma_f32_16x16x32_bf16 v[12:15], v[156:159], v[230:233], v[12:15]
	v_mfma_f32_16x16x32_bf16 v[8:11], v[170:173], v[230:233], v[8:11]
	s_setprio 0
	s_setprio 1
	v_mfma_f32_16x16x32_bf16 v[60:63], v[160:163], v[210:213], v[60:63]
	v_mfma_f32_16x16x32_bf16 v[56:59], v[182:185], v[210:213], v[56:59]
	v_mfma_f32_16x16x32_bf16 v[44:47], v[160:163], v[218:221], v[44:47]
	v_mfma_f32_16x16x32_bf16 v[40:43], v[182:185], v[218:221], v[40:43]
	v_mfma_f32_16x16x32_bf16 v[28:31], v[160:163], v[226:229], v[28:31]
	v_mfma_f32_16x16x32_bf16 v[24:27], v[182:185], v[226:229], v[24:27]
	v_mfma_f32_16x16x32_bf16 v[12:15], v[160:163], v[234:237], v[12:15]
	v_mfma_f32_16x16x32_bf16 v[8:11], v[182:185], v[234:237], v[8:11]
	s_setprio 0
	s_setprio 1
	v_mfma_f32_16x16x32_bf16 v[52:55], v[186:189], v[206:209], v[52:55]
	v_mfma_f32_16x16x32_bf16 v[48:51], v[198:201], v[206:209], v[48:51]
	v_mfma_f32_16x16x32_bf16 v[36:39], v[186:189], v[214:217], v[36:39]
	v_mfma_f32_16x16x32_bf16 v[32:35], v[198:201], v[214:217], v[32:35]
	v_mfma_f32_16x16x32_bf16 v[20:23], v[186:189], v[222:225], v[20:23]
	v_mfma_f32_16x16x32_bf16 v[16:19], v[198:201], v[222:225], v[16:19]
	v_mfma_f32_16x16x32_bf16 v[4:7], v[186:189], v[230:233], v[4:7]
	v_mfma_f32_16x16x32_bf16 v[0:3], v[198:201], v[230:233], v[0:3]
	s_setprio 0
	s_setprio 1
	v_mfma_f32_16x16x32_bf16 v[52:55], v[194:197], v[210:213], v[52:55]
	v_mfma_f32_16x16x32_bf16 v[48:51], v[202:205], v[210:213], v[48:51]
	v_mfma_f32_16x16x32_bf16 v[36:39], v[194:197], v[218:221], v[36:39]
	v_mfma_f32_16x16x32_bf16 v[32:35], v[202:205], v[218:221], v[32:35]
	v_mfma_f32_16x16x32_bf16 v[20:23], v[194:197], v[226:229], v[20:23]
	v_mfma_f32_16x16x32_bf16 v[16:19], v[202:205], v[226:229], v[16:19]
	v_mfma_f32_16x16x32_bf16 v[4:7], v[194:197], v[234:237], v[4:7]
	v_mfma_f32_16x16x32_bf16 v[0:3], v[202:205], v[234:237], v[0:3]
	s_setprio 0
	s_barrier
	s_add_i32 s4, s4, 2
	s_add_u32 vcc_lo, vcc_lo, 0x100
	s_addc_u32 vcc_hi, vcc_hi, 0
	s_cmpk_gt_u32 s4, 0x55
	s_mov_b64 s[42:43], s[54:55]
	s_cbranch_scc0 .LBB0_679
	s_and_b64 vcc, exec, s[50:51]
	s_cbranch_vccz .LBB0_682
	s_barrier

; #define PG8_STAGE(bufoff, gbase, voff) do { _Pragma("unroll") for (int _i = 0; _i < 2; ++_i) \
;         __builtin_amdgcn_global_load_lds((const unsigned*)((const char*)(gbase) + (voff)[_i]), (LAS unsigned*)(lds + (bufoff) + ldsw + _i * 8192), 16, 0, PG8_AUX); } while (0)
; #define PG8_LDA(dst, b, h) do { _Pragma("unroll") for (int m = 0; m < 4; ++m) _Pragma("unroll") for (int k = 0; k < 2; ++k) dst[m][k] = *(const LAS bf16x8*)(lds + PG8_SA(b, h) + aoff + m * 2048 + k * 1024); } while (0)
; #define PG8_LDB(dst, b, h) do { _Pragma("unroll") for (int n = 0; n < 2; ++n) _Pragma("unroll") for (int k = 0; k < 2; ++k) dst[n][k] = *(const LAS bf16x8*)(lds + PG8_SB(b, h) + boff + n * 2048 + k * 1024); } while (0)
; #define PG8_MMA(ai, bj, At, Bt) do { __builtin_amdgcn_s_setprio(1); _Pragma("unroll") for (int m = 0; m < 4; ++m) _Pragma("unroll") for (int n = 0; n < 2; ++n) _Pragma("unroll") for (int k = 0; k < 2; ++k) \
;         acc[ai][bj][m][n] = __builtin_amdgcn_mfma_f32_16x16x32_bf16(Bt[n][k], At[m][k], acc[ai][bj][m][n], 0, 0, 0); __builtin_amdgcn_s_setprio(0); } while (0)
; #define PG8_WAIT_V(n) asm volatile("s_waitcnt vmcnt(" #n ")" ::: "memory")
; #define PG8_WAIT_L(n) asm volatile("s_waitcnt lgkmcnt(" #n ")" ::: "memory")
; #define PG8_BAR __builtin_amdgcn_s_barrier()
; #define PG8_SCHED __builtin_amdgcn_sched_barrier(0)
; template <class Epi, class Sched>
; __device__ __forceinline__ void gemm_phase(LAS unsigned char* lds, const Gemm g, const Sched& S, const Epi& E) {
;     ...
;         for (int t = 0; t < nt; t += 2) {
;             const bool last = (t == nt - 2);
;             const char* a1 = cA + (size_t)(t + 1) * kstep;
;             const char* a2 = last ? nA : cA + (size_t)(t + 2) * kstep; const char* b2 = last ? nB : cB + (size_t)(t + 2) * kstep;
;             const char* a3 = a2 + kstep; const char* b3 = b2 + kstep;
;     ...
;             PG8_LDB(B0, 0, 0); PG8_LDB(B1, 0, 1); PG8_SCHED; PG8_LDA(At, 0, 0); PG8_STAGE(PG8_SA(1, 1), a1 + hstepA, voffA);
;             PG8_WAIT_V(8); PG8_WAIT_L(0); PG8_BAR; PG8_MMA(0, 0, At, B0); PG8_MMA(0, 1, At, B1); PG8_BAR; PG8_SCHED;
;             PG8_LDA(At, 0, 1); PG8_STAGE(PG8_SB(0, 0), b2, voffB); PG8_STAGE(PG8_SB(0, 1), b2 + hstepB, voffB); PG8_STAGE(PG8_SA(0, 0), a2, voffA);
;             PG8_WAIT_V(8); PG8_WAIT_L(0); PG8_BAR; PG8_MMA(1, 0, At, B0); PG8_MMA(1, 1, At, B1); PG8_BAR; PG8_SCHED;
.LBB0_745:
	s_add_u32 s4, s22, 0xfff80080
	s_addc_u32 s52, s23, -1
	s_add_i32 s78, 0, 0x10000
	s_cmp_eq_u32 s94, 28
	s_cselect_b32 s55, s45, s52
	s_cselect_b32 s54, s60, s4
	v_add_u32_e32 v160, s78, v163
	s_cselect_b32 s53, s47, s92
	s_cselect_b32 s52, s61, s65
	s_add_i32 s4, 0, 0x14000
	ds_read_b128 v[156:159], v160
	ds_read_b128 v[166:169], v160 offset:1024
	ds_read_b128 v[170:173], v160 offset:2048
	ds_read_b128 v[182:185], v160 offset:3072
	v_add_u32_e32 v160, s4, v163
	ds_read_b128 v[186:189], v160
	ds_read_b128 v[194:197], v160 offset:1024
	ds_read_b128 v[198:201], v160 offset:2048
	ds_read_b128 v[202:205], v160 offset:3072
	v_lshl_add_u64 v[160:161], s[22:23], 0, v[134:135]
	s_add_i32 m0, s36, 0xc000
	ds_read_b128 v[206:209], v165
	ds_read_b128 v[210:213], v165 offset:1024
	ds_read_b128 v[214:217], v165 offset:2048
	ds_read_b128 v[218:221], v165 offset:3072
	ds_read_b128 v[222:225], v165 offset:4096
	ds_read_b128 v[226:229], v165 offset:5120
	ds_read_b128 v[230:233], v165 offset:6144
	ds_read_b128 v[234:237], v165 offset:7168
	global_load_lds_dwordx4 v[160:161], off
	v_lshl_add_u64 v[160:161], s[22:23], 0, v[154:155]
	s_add_i32 m0, s36, 0xe000
	s_nop 0
	global_load_lds_dwordx4 v[160:161], off
	s_waitcnt vmcnt(8)
	s_waitcnt lgkmcnt(0)
	s_barrier
	s_setprio 1
	s_waitcnt lgkmcnt(0)
	v_mfma_f32_16x16x32_bf16 v[124:127], v[156:159], v[206:209], v[124:127]
	v_mfma_f32_16x16x32_bf16 v[116:119], v[170:173], v[206:209], v[116:119]
	v_mfma_f32_16x16x32_bf16 v[108:111], v[156:159], v[214:217], v[108:111]
	v_mfma_f32_16x16x32_bf16 v[100:103], v[170:173], v[214:217], v[100:103]
	v_mfma_f32_16x16x32_bf16 v[92:95], v[156:159], v[222:225], v[92:95]
	v_mfma_f32_16x16x32_bf16 v[84:87], v[170:173], v[222:225], v[84:87]
	v_mfma_f32_16x16x32_bf16 v[76:79], v[156:159], v[230:233], v[76:79]
	v_mfma_f32_16x16x32_bf16 v[68:71], v[170:173], v[230:233], v[68:71]
	s_setprio 0
	s_setprio 1
	v_mfma_f32_16x16x32_bf16 v[124:127], v[166:169], v[210:213], v[124:127]
	v_mfma_f32_16x16x32_bf16 v[116:119], v[182:185], v[210:213], v[116:119]
	v_mfma_f32_16x16x32_bf16 v[108:111], v[166:169], v[218:221], v[108:111]
	v_mfma_f32_16x16x32_bf16 v[100:103], v[182:185], v[218:221], v[100:103]
	v_mfma_f32_16x16x32_bf16 v[92:95], v[166:169], v[226:229], v[92:95]
	v_mfma_f32_16x16x32_bf16 v[84:87], v[182:185], v[226:229], v[84:87]
	v_mfma_f32_16x16x32_bf16 v[76:79], v[166:169], v[234:237], v[76:79]
	v_mfma_f32_16x16x32_bf16 v[68:71], v[182:185], v[234:237], v[68:71]
	s_setprio 0
	s_setprio 1
	v_mfma_f32_16x16x32_bf16 v[120:123], v[186:189], v[206:209], v[120:123]
	v_mfma_f32_16x16x32_bf16 v[112:115], v[198:201], v[206:209], v[112:115]
	v_mfma_f32_16x16x32_bf16 v[104:107], v[186:189], v[214:217], v[104:107]
	v_mfma_f32_16x16x32_bf16 v[96:99], v[198:201], v[214:217], v[96:99]
	v_mfma_f32_16x16x32_bf16 v[88:91], v[186:189], v[222:225], v[88:91]
	v_mfma_f32_16x16x32_bf16 v[80:83], v[198:201], v[222:225], v[80:83]
	v_mfma_f32_16x16x32_bf16 v[72:75], v[186:189], v[230:233], v[72:75]
	v_mfma_f32_16x16x32_bf16 v[64:67], v[198:201], v[230:233], v[64:67]
	s_setprio 0
	s_setprio 1
	v_mfma_f32_16x16x32_bf16 v[120:123], v[194:197], v[210:213], v[120:123]
	v_mfma_f32_16x16x32_bf16 v[112:115], v[202:205], v[210:213], v[112:115]
	v_mfma_f32_16x16x32_bf16 v[104:107], v[194:197], v[218:221], v[104:107]
	v_mfma_f32_16x16x32_bf16 v[96:99], v[202:205], v[218:221], v[96:99]
	v_mfma_f32_16x16x32_bf16 v[88:91], v[194:197], v[226:229], v[88:91]
	v_mfma_f32_16x16x32_bf16 v[80:83], v[202:205], v[226:229], v[80:83]
	v_mfma_f32_16x16x32_bf16 v[72:75], v[194:197], v[234:237], v[72:75]
	v_mfma_f32_16x16x32_bf16 v[64:67], v[202:205], v[234:237], v[64:67]
	s_setprio 0
	s_barrier
	s_add_i32 s78, s78, s34
	v_lshl_add_u64 v[160:161], s[52:53], 0, v[136:137]
	s_mov_b32 m0, s78
	ds_read_b128 v[206:209], v165 offset:16384
	ds_read_b128 v[210:213], v165 offset:17408
	ds_read_b128 v[214:217], v165 offset:18432
	ds_read_b128 v[218:221], v165 offset:19456
	ds_read_b128 v[222:225], v165 offset:20480
	ds_read_b128 v[226:229], v165 offset:21504
	ds_read_b128 v[230:233], v165 offset:22528
	ds_read_b128 v[234:237], v165 offset:23552
	global_load_lds_dwordx4 v[160:161], off
	s_add_i32 m0, s78, 0x2000
	s_add_u32 vcc_lo, s52, 0x80000
	v_lshl_add_u64 v[190:191], s[52:53], 0, v[128:129]
	s_addc_u32 vcc_hi, s53, 0
	s_add_i32 s4, s4, s34
	global_load_lds_dwordx4 v[190:191], off
	v_lshl_add_u64 v[240:241], s[54:55], 0, v[130:131]
	v_lshl_add_u64 v[238:239], s[54:55], 0, v[132:133]
	s_mov_b32 m0, s36
	s_nop 0
	global_load_lds_dwordx4 v[238:239], off
	s_mov_b32 m0, s56
	s_nop 0
	global_load_lds_dwordx4 v[240:241], off
	s_waitcnt vmcnt(6)
	s_waitcnt lgkmcnt(0)
	s_barrier
; #define PG8_STAGE(bufoff, gbase, voff) do { _Pragma("unroll") for (int _i = 0; _i < 2; ++_i) \
;         __builtin_amdgcn_global_load_lds((const unsigned*)((const char*)(gbase) + (voff)[_i]), (LAS unsigned*)(lds + (bufoff) + ldsw + _i * 8192), 16, 0, PG8_AUX); } while (0)
; #define PG8_LDA(dst, b, h) do { _Pragma("unroll") for (int m = 0; m < 4; ++m) _Pragma("unroll") for (int k = 0; k < 2; ++k) dst[m][k] = *(const LAS bf16x8*)(lds + PG8_SA(b, h) + aoff + m * 2048 + k * 1024); } while (0)
; #define PG8_LDB(dst, b, h) do { _Pragma("unroll") for (int n = 0; n < 2; ++n) _Pragma("unroll") for (int k = 0; k < 2; ++k) dst[n][k] = *(const LAS bf16x8*)(lds + PG8_SB(b, h) + boff + n * 2048 + k * 1024); } while (0)
; #define PG8_MMA(ai, bj, At, Bt) do { __builtin_amdgcn_s_setprio(1); _Pragma("unroll") for (int m = 0; m < 4; ++m) _Pragma("unroll") for (int n = 0; n < 2; ++n) _Pragma("unroll") for (int k = 0; k < 2; ++k) \
;         acc[ai][bj][m][n] = __builtin_amdgcn_mfma_f32_16x16x32_bf16(Bt[n][k], At[m][k], acc[ai][bj][m][n], 0, 0, 0); __builtin_amdgcn_s_setprio(0); } while (0)
; #define PG8_WAIT_V(n) asm volatile("s_waitcnt vmcnt(" #n ")" ::: "memory")
; #define PG8_WAIT_L(n) asm volatile("s_waitcnt lgkmcnt(" #n ")" ::: "memory")
; #define PG8_BAR __builtin_amdgcn_s_barrier()
; #define PG8_SCHED __builtin_amdgcn_sched_barrier(0)
; template <class Epi, class Sched>
; __device__ __forceinline__ void gemm_phase(LAS unsigned char* lds, const Gemm g, const Sched& S, const Epi& E) {
;     ...
;             PG8_WAIT_V(8); PG8_WAIT_L(0); PG8_BAR; PG8_MMA(1, 0, At, B0); PG8_MMA(1, 1, At, B1); PG8_BAR; PG8_SCHED;
;             PG8_LDB(B0, 1, 0); PG8_LDB(B1, 1, 1); PG8_SCHED; PG8_LDA(At, 1, 0); PG8_STAGE(PG8_SA(0, 1), a2 + hstepA, voffA);
;             PG8_WAIT_V(8); PG8_WAIT_L(0); PG8_BAR; PG8_MMA(0, 0, At, B0); PG8_MMA(0, 1, At, B1); PG8_BAR; PG8_SCHED;
	s_setprio 1
	s_waitcnt lgkmcnt(0)
	v_mfma_f32_16x16x32_bf16 v[60:63], v[156:159], v[206:209], v[60:63]
	v_mfma_f32_16x16x32_bf16 v[52:55], v[170:173], v[206:209], v[52:55]
	v_mfma_f32_16x16x32_bf16 v[44:47], v[156:159], v[214:217], v[44:47]
	v_mfma_f32_16x16x32_bf16 v[36:39], v[170:173], v[214:217], v[36:39]
	v_mfma_f32_16x16x32_bf16 v[28:31], v[156:159], v[222:225], v[28:31]
	v_mfma_f32_16x16x32_bf16 v[20:23], v[170:173], v[222:225], v[20:23]
	v_mfma_f32_16x16x32_bf16 v[12:15], v[156:159], v[230:233], v[12:15]
	v_mfma_f32_16x16x32_bf16 v[4:7], v[170:173], v[230:233], v[4:7]
	s_setprio 0
	s_setprio 1
	v_mfma_f32_16x16x32_bf16 v[60:63], v[166:169], v[210:213], v[60:63]
	v_mfma_f32_16x16x32_bf16 v[52:55], v[182:185], v[210:213], v[52:55]
	v_mfma_f32_16x16x32_bf16 v[44:47], v[166:169], v[218:221], v[44:47]
	v_mfma_f32_16x16x32_bf16 v[36:39], v[182:185], v[218:221], v[36:39]
	v_mfma_f32_16x16x32_bf16 v[28:31], v[166:169], v[226:229], v[28:31]
	v_mfma_f32_16x16x32_bf16 v[20:23], v[182:185], v[226:229], v[20:23]
	v_mfma_f32_16x16x32_bf16 v[12:15], v[166:169], v[234:237], v[12:15]
	v_mfma_f32_16x16x32_bf16 v[4:7], v[182:185], v[234:237], v[4:7]
	s_setprio 0
	s_setprio 1
	v_mfma_f32_16x16x32_bf16 v[56:59], v[186:189], v[206:209], v[56:59]
	v_mfma_f32_16x16x32_bf16 v[48:51], v[198:201], v[206:209], v[48:51]
	v_mfma_f32_16x16x32_bf16 v[40:43], v[186:189], v[214:217], v[40:43]
	v_mfma_f32_16x16x32_bf16 v[32:35], v[198:201], v[214:217], v[32:35]
	v_mfma_f32_16x16x32_bf16 v[24:27], v[186:189], v[222:225], v[24:27]
	v_mfma_f32_16x16x32_bf16 v[16:19], v[198:201], v[222:225], v[16:19]
	v_mfma_f32_16x16x32_bf16 v[8:11], v[186:189], v[230:233], v[8:11]
	v_mfma_f32_16x16x32_bf16 v[0:3], v[198:201], v[230:233], v[0:3]
	s_setprio 0
	s_setprio 1
	v_mfma_f32_16x16x32_bf16 v[56:59], v[194:197], v[210:213], v[56:59]
	v_mfma_f32_16x16x32_bf16 v[48:51], v[202:205], v[210:213], v[48:51]
	v_mfma_f32_16x16x32_bf16 v[40:43], v[194:197], v[218:221], v[40:43]
	v_mfma_f32_16x16x32_bf16 v[32:35], v[202:205], v[218:221], v[32:35]
	v_mfma_f32_16x16x32_bf16 v[24:27], v[194:197], v[226:229], v[24:27]
	v_mfma_f32_16x16x32_bf16 v[16:19], v[202:205], v[226:229], v[16:19]
	v_mfma_f32_16x16x32_bf16 v[8:11], v[194:197], v[234:237], v[8:11]
	v_mfma_f32_16x16x32_bf16 v[0:3], v[202:205], v[234:237], v[0:3]
	s_setprio 0
	s_barrier
	s_add_i32 s4, 0, 0x18000
	v_add_u32_e32 v181, s4, v163
	s_add_i32 s78, 0, 0x1c000
	ds_read_b128 v[156:159], v181
	ds_read_b128 v[166:169], v181 offset:1024
	ds_read_b128 v[170:173], v181 offset:2048
	ds_read_b128 v[182:185], v181 offset:3072
	v_add_u32_e32 v181, s78, v163
	ds_read_b128 v[186:189], v181
	ds_read_b128 v[194:197], v181 offset:1024
	ds_read_b128 v[198:201], v181 offset:2048
	ds_read_b128 v[202:205], v181 offset:3072
	s_add_u32 s54, s54, 0x80000
	s_addc_u32 s55, s55, 0
	s_mov_b32 m0, s57
	v_lshl_add_u64 v[242:243], s[54:55], 0, v[132:133]
	ds_read_b128 v[206:209], v165 offset:32768
	ds_read_b128 v[210:213], v165 offset:33792
	ds_read_b128 v[214:217], v165 offset:34816
	ds_read_b128 v[218:221], v165 offset:35840
	ds_read_b128 v[222:225], v165 offset:36864
	ds_read_b128 v[226:229], v165 offset:37888
	ds_read_b128 v[230:233], v165 offset:38912
	ds_read_b128 v[234:237], v165 offset:39936
	s_add_u32 s100, s52, 0x80000
	s_addc_u32 s101, s53, 0
	s_add_i32 m0, s34, 0x14000
	s_nop 0
	global_load_lds_dwordx4 v136, s[100:101]
	s_add_i32 m0, s34, 0x16000
	s_nop 0
	global_load_lds_dwordx4 v128, s[100:101]
	s_mov_b32 m0, s57
	s_nop 0
	global_load_lds_dwordx4 v[242:243], off
	v_lshl_add_u64 v[242:243], s[54:55], 0, v[130:131]
	s_mov_b32 m0, s62
	s_nop 0
	global_load_lds_dwordx4 v[242:243], off
	s_waitcnt vmcnt(8)
	s_waitcnt lgkmcnt(0)
	s_barrier
	s_setprio 1
	s_waitcnt lgkmcnt(0)
	v_mfma_f32_16x16x32_bf16 v[124:127], v[156:159], v[206:209], v[124:127]
	v_mfma_f32_16x16x32_bf16 v[116:119], v[170:173], v[206:209], v[116:119]
	v_mfma_f32_16x16x32_bf16 v[108:111], v[156:159], v[214:217], v[108:111]
	v_mfma_f32_16x16x32_bf16 v[100:103], v[170:173], v[214:217], v[100:103]
	v_mfma_f32_16x16x32_bf16 v[92:95], v[156:159], v[222:225], v[92:95]
	v_mfma_f32_16x16x32_bf16 v[84:87], v[170:173], v[222:225], v[84:87]
	v_mfma_f32_16x16x32_bf16 v[76:79], v[156:159], v[230:233], v[76:79]
	v_mfma_f32_16x16x32_bf16 v[68:71], v[170:173], v[230:233], v[68:71]
	s_setprio 0
	s_setprio 1
	v_mfma_f32_16x16x32_bf16 v[124:127], v[166:169], v[210:213], v[124:127]
	v_mfma_f32_16x16x32_bf16 v[116:119], v[182:185], v[210:213], v[116:119]
	v_mfma_f32_16x16x32_bf16 v[108:111], v[166:169], v[218:221], v[108:111]
	v_mfma_f32_16x16x32_bf16 v[100:103], v[182:185], v[218:221], v[100:103]
	v_mfma_f32_16x16x32_bf16 v[92:95], v[166:169], v[226:229], v[92:95]
	v_mfma_f32_16x16x32_bf16 v[84:87], v[182:185], v[226:229], v[84:87]
	v_mfma_f32_16x16x32_bf16 v[76:79], v[166:169], v[234:237], v[76:79]
	v_mfma_f32_16x16x32_bf16 v[68:71], v[182:185], v[234:237], v[68:71]
	s_setprio 0
	s_setprio 1
	v_mfma_f32_16x16x32_bf16 v[120:123], v[186:189], v[206:209], v[120:123]
	v_mfma_f32_16x16x32_bf16 v[112:115], v[198:201], v[206:209], v[112:115]
	v_mfma_f32_16x16x32_bf16 v[104:107], v[186:189], v[214:217], v[104:107]
	v_mfma_f32_16x16x32_bf16 v[96:99], v[198:201], v[214:217], v[96:99]
	v_mfma_f32_16x16x32_bf16 v[88:91], v[186:189], v[222:225], v[88:91]
	v_mfma_f32_16x16x32_bf16 v[80:83], v[198:201], v[222:225], v[80:83]
	v_mfma_f32_16x16x32_bf16 v[72:75], v[186:189], v[230:233], v[72:75]
	v_mfma_f32_16x16x32_bf16 v[64:67], v[198:201], v[230:233], v[64:67]
	s_setprio 0
	s_setprio 1
	v_mfma_f32_16x16x32_bf16 v[120:123], v[194:197], v[210:213], v[120:123]
	v_mfma_f32_16x16x32_bf16 v[112:115], v[202:205], v[210:213], v[112:115]
	v_mfma_f32_16x16x32_bf16 v[104:107], v[194:197], v[218:221], v[104:107]
	v_mfma_f32_16x16x32_bf16 v[96:99], v[202:205], v[218:221], v[96:99]
	v_mfma_f32_16x16x32_bf16 v[88:91], v[194:197], v[226:229], v[88:91]
	v_mfma_f32_16x16x32_bf16 v[80:83], v[202:205], v[226:229], v[80:83]
	v_mfma_f32_16x16x32_bf16 v[72:75], v[194:197], v[234:237], v[72:75]
	v_mfma_f32_16x16x32_bf16 v[64:67], v[202:205], v[234:237], v[64:67]
	s_setprio 0
	s_barrier
; #define PG8_STAGE(bufoff, gbase, voff) do { _Pragma("unroll") for (int _i = 0; _i < 2; ++_i) \
;         __builtin_amdgcn_global_load_lds((const unsigned*)((const char*)(gbase) + (voff)[_i]), (LAS unsigned*)(lds + (bufoff) + ldsw + _i * 8192), 16, 0, PG8_AUX); } while (0)
; #define PG8_LDA(dst, b, h) do { _Pragma("unroll") for (int m = 0; m < 4; ++m) _Pragma("unroll") for (int k = 0; k < 2; ++k) dst[m][k] = *(const LAS bf16x8*)(lds + PG8_SA(b, h) + aoff + m * 2048 + k * 1024); } while (0)
; #define PG8_MMA(ai, bj, At, Bt) do { __builtin_amdgcn_s_setprio(1); _Pragma("unroll") for (int m = 0; m < 4; ++m) _Pragma("unroll") for (int n = 0; n < 2; ++n) _Pragma("unroll") for (int k = 0; k < 2; ++k) \
;         acc[ai][bj][m][n] = __builtin_amdgcn_mfma_f32_16x16x32_bf16(Bt[n][k], At[m][k], acc[ai][bj][m][n], 0, 0, 0); __builtin_amdgcn_s_setprio(0); } while (0)
; #define PG8_WAIT_V(n) asm volatile("s_waitcnt vmcnt(" #n ")" ::: "memory")
; #define PG8_WAIT_L(n) asm volatile("s_waitcnt lgkmcnt(" #n ")" ::: "memory")
; #define PG8_BAR __builtin_amdgcn_s_barrier()
; #define PG8_SCHED __builtin_amdgcn_sched_barrier(0)
; template <class Epi, class Sched>
; __device__ __forceinline__ void gemm_phase(LAS unsigned char* lds, const Gemm g, const Sched& S, const Epi& E) {
;     ...
;             PG8_LDA(At, 1, 1); PG8_STAGE(PG8_SB(1, 0), b3, voffB); PG8_STAGE(PG8_SB(1, 1), b3 + hstepB, voffB); PG8_STAGE(PG8_SA(1, 0), a3, voffA);
;             PG8_WAIT_V(8); PG8_WAIT_L(0); PG8_BAR; PG8_MMA(1, 0, At, B0); PG8_MMA(1, 1, At, B1); PG8_BAR; PG8_SCHED;
	s_add_i32 s4, s4, s34
	v_lshl_add_u64 v[160:161], v[160:161], 0, s[12:13]
	s_mov_b32 m0, s4
	ds_read_b128 v[206:209], v165 offset:49152
	ds_read_b128 v[210:213], v165 offset:50176
	ds_read_b128 v[214:217], v165 offset:51200
	ds_read_b128 v[218:221], v165 offset:52224
	ds_read_b128 v[222:225], v165 offset:53248
	ds_read_b128 v[226:229], v165 offset:54272
	ds_read_b128 v[230:233], v165 offset:55296
	ds_read_b128 v[234:237], v165 offset:56320
	global_load_lds_dwordx4 v[160:161], off
	s_add_i32 m0, s4, 0x2000
	s_add_u32 s52, s52, 0x80080
	v_lshl_add_u64 v[160:161], v[190:191], 0, s[12:13]
	s_addc_u32 s53, s53, 0
	s_add_i32 s4, s78, s34
	global_load_lds_dwordx4 v[160:161], off
	v_lshl_add_u64 v[160:161], s[52:53], 0, v[136:137]
	s_mov_b32 m0, s4
	s_nop 0
	global_load_lds_dwordx4 v[160:161], off
	v_lshl_add_u64 v[160:161], s[52:53], 0, v[128:129]
	s_add_i32 m0, s4, 0x2000
	s_nop 0
	global_load_lds_dwordx4 v[160:161], off
	v_lshl_add_u64 v[160:161], v[238:239], 0, s[12:13]
	s_mov_b32 m0, s63
	s_nop 0
	global_load_lds_dwordx4 v[160:161], off
	v_lshl_add_u64 v[160:161], v[240:241], 0, s[12:13]
	s_mov_b32 m0, s64
	s_nop 0
	global_load_lds_dwordx4 v[160:161], off
	s_waitcnt vmcnt(8)
	s_waitcnt lgkmcnt(0)
	s_barrier
	s_setprio 1
	s_waitcnt lgkmcnt(0)
	v_mfma_f32_16x16x32_bf16 v[60:63], v[156:159], v[206:209], v[60:63]
	v_mfma_f32_16x16x32_bf16 v[52:55], v[170:173], v[206:209], v[52:55]
	v_mfma_f32_16x16x32_bf16 v[44:47], v[156:159], v[214:217], v[44:47]
	v_mfma_f32_16x16x32_bf16 v[36:39], v[170:173], v[214:217], v[36:39]
	v_mfma_f32_16x16x32_bf16 v[28:31], v[156:159], v[222:225], v[28:31]
	v_mfma_f32_16x16x32_bf16 v[20:23], v[170:173], v[222:225], v[20:23]
	v_mfma_f32_16x16x32_bf16 v[12:15], v[156:159], v[230:233], v[12:15]
	v_mfma_f32_16x16x32_bf16 v[4:7], v[170:173], v[230:233], v[4:7]
	s_setprio 0
	s_setprio 1
	v_mfma_f32_16x16x32_bf16 v[60:63], v[166:169], v[210:213], v[60:63]
	v_mfma_f32_16x16x32_bf16 v[52:55], v[182:185], v[210:213], v[52:55]
	v_mfma_f32_16x16x32_bf16 v[44:47], v[166:169], v[218:221], v[44:47]
	v_mfma_f32_16x16x32_bf16 v[36:39], v[182:185], v[218:221], v[36:39]
	v_mfma_f32_16x16x32_bf16 v[28:31], v[166:169], v[226:229], v[28:31]
	v_mfma_f32_16x16x32_bf16 v[20:23], v[182:185], v[226:229], v[20:23]
	v_mfma_f32_16x16x32_bf16 v[12:15], v[166:169], v[234:237], v[12:15]
	v_mfma_f32_16x16x32_bf16 v[4:7], v[182:185], v[234:237], v[4:7]
	s_setprio 0
	s_setprio 1
	v_mfma_f32_16x16x32_bf16 v[56:59], v[186:189], v[206:209], v[56:59]
	v_mfma_f32_16x16x32_bf16 v[48:51], v[198:201], v[206:209], v[48:51]
	v_mfma_f32_16x16x32_bf16 v[40:43], v[186:189], v[214:217], v[40:43]
	v_mfma_f32_16x16x32_bf16 v[32:35], v[198:201], v[214:217], v[32:35]
	v_mfma_f32_16x16x32_bf16 v[24:27], v[186:189], v[222:225], v[24:27]
	v_mfma_f32_16x16x32_bf16 v[16:19], v[198:201], v[222:225], v[16:19]
	v_mfma_f32_16x16x32_bf16 v[8:11], v[186:189], v[230:233], v[8:11]
	v_mfma_f32_16x16x32_bf16 v[0:3], v[198:201], v[230:233], v[0:3]
	s_setprio 0
	s_setprio 1
	v_mfma_f32_16x16x32_bf16 v[56:59], v[194:197], v[210:213], v[56:59]
	v_mfma_f32_16x16x32_bf16 v[48:51], v[202:205], v[210:213], v[48:51]
	v_mfma_f32_16x16x32_bf16 v[40:43], v[194:197], v[218:221], v[40:43]
	v_mfma_f32_16x16x32_bf16 v[32:35], v[202:205], v[218:221], v[32:35]
	v_mfma_f32_16x16x32_bf16 v[24:27], v[194:197], v[226:229], v[24:27]
	v_mfma_f32_16x16x32_bf16 v[16:19], v[202:205], v[226:229], v[16:19]
	v_mfma_f32_16x16x32_bf16 v[8:11], v[194:197], v[234:237], v[8:11]
	v_mfma_f32_16x16x32_bf16 v[0:3], v[202:205], v[234:237], v[0:3]
	s_setprio 0
	s_barrier
	s_add_i32 s94, s94, 2
	s_add_u32 s22, s22, 0x100
	s_addc_u32 s23, s23, 0
	s_add_u32 s65, s65, 0x100
	s_addc_u32 s92, s92, 0
	s_cmp_gt_u32 s94, 29
	s_cbranch_scc0 .LBB0_745
	s_and_b64 vcc, exec, s[42:43]
	s_cbranch_vccz .LBB0_748
	s_barrier
